# v125 plus the two per-iteration LDS address re-computations of every GEMM K-loop folded into ds_read offsets from loop-invariant registers (no VALU left in the load segments)
# speedup vs baseline: 1.0070x; 1.0005x over previous
; #define PG8_STAGE(bufoff, gbase, voff) do { _Pragma("unroll") for (int _i = 0; _i < 2; ++_i) \
;         __builtin_amdgcn_global_load_lds((const unsigned*)((const char*)(gbase) + (voff)[_i]), (PG8_LAS unsigned*)(lds + (bufoff) + ldsw + _i * 8192), 16, 0, 0); } while (0)
; #define PG8_LDA(dst, b, h) do { _Pragma("unroll") for (int m = 0; m < 4; ++m) _Pragma("unroll") for (int k = 0; k < 2; ++k) dst[m][k] = *(const PG8_LAS bf16x8*)(lds + PG8_SA(b, h) + aoff + m * 2048 + k * 1024); } while (0)
; #define PG8_LDB(dst, b, h) do { _Pragma("unroll") for (int n = 0; n < 2; ++n) _Pragma("unroll") for (int k = 0; k < 2; ++k) dst[n][k] = *(const PG8_LAS bf16x8*)(lds + PG8_SB(b, h) + boff + n * 2048 + k * 1024); } while (0)
; #define PG8_MMA(ai, bj, At, Bt) do { __builtin_amdgcn_s_setprio(1); _Pragma("unroll") for (int m = 0; m < 4; ++m) _Pragma("unroll") for (int n = 0; n < 2; ++n) _Pragma("unroll") for (int k = 0; k < 2; ++k) \
;         acc[ai][bj][m][n] = __builtin_amdgcn_mfma_f32_16x16x32_bf16(Bt[n][k], At[m][k], acc[ai][bj][m][n], 0, 0, 0); __builtin_amdgcn_s_setprio(0); } while (0)
; #define PG8_WAIT_V(n) asm volatile("s_waitcnt vmcnt(" #n ")" ::: "memory")
; #define PG8_WAIT_L(n) asm volatile("s_waitcnt lgkmcnt(" #n ")" ::: "memory")
; template <class Epi, class Sched, bool ALIGN_EPI = false, bool SP2 = false>
; __device__ __forceinline__ void gemm_phase(PG8_LAS unsigned char* lds, const Gemm g, const Sched& S, const Epi& E) {
;     ...
;             const bool last = (t == nt - 2);
;             const char* a1 = cA + (size_t)(t + 1) * kstep;
;             const char* a2 = last ? nA : cA + (size_t)(t + 2) * kstep; const char* b2 = last ? nB : cB + (size_t)(t + 2) * kstep;
;             const char* a3 = a2 + kstep; const char* b3 = b2 + kstep;
;             if (last && has_next) S.a_ready(nxt);
;             if constexpr (SP2) {
;             PG8_LDB(B0, 0, 0); PG8_LDB(B1, 0, 1); PG8_SCHED; PG8_LDA(At, 0, 0); PG8_STAGE(PG8_SA(1, 1), a1 + hstep, voffA);
;             PG8_WAIT_V(8); PG8_WAIT_L(0); PG8_BAR; PG8_MMA(0, 0, At, B0); PG8_MMA(0, 1, At, B1); PG8_BAR; PG8_SCHED;
;             PG8_LDA(At, 0, 1); PG8_STAGE(PG8_SB(0, 0), b2, voffB); PG8_STAGE(PG8_SB(0, 1), b2 + hstep, voffB); PG8_STAGE(PG8_SA(0, 0), a2, voffA);
;             PG8_WAIT_V(8); PG8_WAIT_L(0); PG8_BAR; PG8_MMA(1, 0, At, B0); PG8_MMA(1, 1, At, B1); PG8_BAR; PG8_SCHED;
.LBB0_102:
	ds_read_b128 v[160:163], v155
	ds_read_b128 v[164:167], v155 offset:1024
	ds_read_b128 v[168:171], v155 offset:2048
	ds_read_b128 v[172:175], v155 offset:3072
	ds_read_b128 v[176:179], v157
	ds_read_b128 v[180:183], v157 offset:1024
	ds_read_b128 v[184:187], v157 offset:2048
	ds_read_b128 v[188:191], v157 offset:3072
	s_add_u32 s62, s74, 0xfff80080
	s_addc_u32 s63, s75, -1
	s_cmp_eq_u32 s90, 28
	s_cselect_b32 s79, s10, s63
	s_cselect_b32 s78, s11, s62
	s_cselect_b32 s77, s51, s89
	s_cselect_b32 s76, s55, s88
	s_add_i32 m0, s61, 0xc000
	ds_read_b128 v[192:195], v159
	ds_read_b128 v[196:199], v159 offset:1024
	ds_read_b128 v[200:203], v159 offset:2048
	ds_read_b128 v[204:207], v159 offset:3072
	ds_read_b128 v[208:211], v159 offset:4096
	ds_read_b128 v[212:215], v159 offset:5120
	ds_read_b128 v[216:219], v159 offset:6144
	ds_read_b128 v[220:223], v159 offset:7168
	global_load_lds_dwordx4 v138, s[74:75]
	s_add_i32 m0, s61, 0xe000
	s_nop 0
	global_load_lds_dwordx4 v140, s[74:75]
	s_waitcnt vmcnt(8)
	s_waitcnt lgkmcnt(0)
	s_setprio 1
	s_barrier
	v_mfma_f32_16x16x32_bf16 v[124:127], v[160:163], v[192:195], v[124:127]
	v_mfma_f32_16x16x32_bf16 v[124:127], v[164:167], v[196:199], v[124:127]
	v_mfma_f32_16x16x32_bf16 v[108:111], v[160:163], v[200:203], v[108:111]
	v_mfma_f32_16x16x32_bf16 v[108:111], v[164:167], v[204:207], v[108:111]
	v_mfma_f32_16x16x32_bf16 v[92:95], v[160:163], v[208:211], v[92:95]
	v_mfma_f32_16x16x32_bf16 v[92:95], v[164:167], v[212:215], v[92:95]
	v_mfma_f32_16x16x32_bf16 v[76:79], v[160:163], v[216:219], v[76:79]
	v_mfma_f32_16x16x32_bf16 v[76:79], v[164:167], v[220:223], v[76:79]
	v_mfma_f32_16x16x32_bf16 v[72:75], v[168:171], v[216:219], v[72:75]
	v_mfma_f32_16x16x32_bf16 v[72:75], v[172:175], v[220:223], v[72:75]
	v_mfma_f32_16x16x32_bf16 v[88:91], v[168:171], v[208:211], v[88:91]
	v_mfma_f32_16x16x32_bf16 v[88:91], v[172:175], v[212:215], v[88:91]
	v_mfma_f32_16x16x32_bf16 v[104:107], v[168:171], v[200:203], v[104:107]
	v_mfma_f32_16x16x32_bf16 v[104:107], v[172:175], v[204:207], v[104:107]
	v_mfma_f32_16x16x32_bf16 v[120:123], v[168:171], v[192:195], v[120:123]
	v_mfma_f32_16x16x32_bf16 v[120:123], v[172:175], v[196:199], v[120:123]
	v_mfma_f32_16x16x32_bf16 v[116:119], v[176:179], v[192:195], v[116:119]
	v_mfma_f32_16x16x32_bf16 v[116:119], v[180:183], v[196:199], v[116:119]
	v_mfma_f32_16x16x32_bf16 v[100:103], v[176:179], v[200:203], v[100:103]
	v_mfma_f32_16x16x32_bf16 v[100:103], v[180:183], v[204:207], v[100:103]
	v_mfma_f32_16x16x32_bf16 v[84:87], v[176:179], v[208:211], v[84:87]
	v_mfma_f32_16x16x32_bf16 v[84:87], v[180:183], v[212:215], v[84:87]
	v_mfma_f32_16x16x32_bf16 v[68:71], v[176:179], v[216:219], v[68:71]
	v_mfma_f32_16x16x32_bf16 v[68:71], v[180:183], v[220:223], v[68:71]
	v_mfma_f32_16x16x32_bf16 v[64:67], v[184:187], v[216:219], v[64:67]
	v_mfma_f32_16x16x32_bf16 v[64:67], v[188:191], v[220:223], v[64:67]
	v_mfma_f32_16x16x32_bf16 v[80:83], v[184:187], v[208:211], v[80:83]
	v_mfma_f32_16x16x32_bf16 v[80:83], v[188:191], v[212:215], v[80:83]
	s_setprio 2
	s_barrier
	v_mfma_f32_16x16x32_bf16 v[96:99], v[184:187], v[200:203], v[96:99]
	v_mfma_f32_16x16x32_bf16 v[96:99], v[188:191], v[204:207], v[96:99]
	v_mfma_f32_16x16x32_bf16 v[112:115], v[184:187], v[192:195], v[112:115]
	v_mfma_f32_16x16x32_bf16 v[112:115], v[188:191], v[196:199], v[112:115]
	s_setprio 0
	s_add_i32 s62, s84, s35
	s_mov_b32 m0, s62
	ds_read_b128 v[192:195], v159 offset:16384
	ds_read_b128 v[196:199], v159 offset:17408
	ds_read_b128 v[200:203], v159 offset:18432
	ds_read_b128 v[204:207], v159 offset:19456
	ds_read_b128 v[208:211], v159 offset:20480
	ds_read_b128 v[212:215], v159 offset:21504
	ds_read_b128 v[216:219], v159 offset:22528
	ds_read_b128 v[220:223], v159 offset:23552
	global_load_lds_dwordx4 v130, s[76:77]
	s_add_i32 m0, s62, 0x2000
	s_add_u32 s92, s76, 0x80000
	s_addc_u32 s93, s77, 0
	s_add_i32 s62, s85, s35
	global_load_lds_dwordx4 v134, s[76:77]
	s_mov_b32 m0, s62
	s_nop 0
	global_load_lds_dwordx4 v130, s[92:93]
	s_add_i32 m0, s62, 0x2000
	s_nop 0
	global_load_lds_dwordx4 v134, s[92:93]
	s_mov_b32 m0, s61
	s_nop 0
	global_load_lds_dwordx4 v128, s[78:79]
	s_mov_b32 m0, s65
	s_nop 0
	global_load_lds_dwordx4 v132, s[78:79]
	s_waitcnt vmcnt(8)
	s_waitcnt lgkmcnt(0)
	s_setprio 1
	s_barrier
	v_mfma_f32_16x16x32_bf16 v[60:63], v[160:163], v[192:195], v[60:63]
	v_mfma_f32_16x16x32_bf16 v[60:63], v[164:167], v[196:199], v[60:63]
	v_mfma_f32_16x16x32_bf16 v[44:47], v[160:163], v[200:203], v[44:47]
	v_mfma_f32_16x16x32_bf16 v[44:47], v[164:167], v[204:207], v[44:47]
	v_mfma_f32_16x16x32_bf16 v[28:31], v[160:163], v[208:211], v[28:31]
	v_mfma_f32_16x16x32_bf16 v[28:31], v[164:167], v[212:215], v[28:31]
	v_mfma_f32_16x16x32_bf16 v[12:15], v[160:163], v[216:219], v[12:15]
	v_mfma_f32_16x16x32_bf16 v[12:15], v[164:167], v[220:223], v[12:15]
	v_mfma_f32_16x16x32_bf16 v[8:11], v[168:171], v[216:219], v[8:11]
	v_mfma_f32_16x16x32_bf16 v[8:11], v[172:175], v[220:223], v[8:11]
	v_mfma_f32_16x16x32_bf16 v[24:27], v[168:171], v[208:211], v[24:27]
	v_mfma_f32_16x16x32_bf16 v[24:27], v[172:175], v[212:215], v[24:27]
	v_mfma_f32_16x16x32_bf16 v[40:43], v[168:171], v[200:203], v[40:43]
	v_mfma_f32_16x16x32_bf16 v[40:43], v[172:175], v[204:207], v[40:43]
	v_mfma_f32_16x16x32_bf16 v[56:59], v[168:171], v[192:195], v[56:59]
	v_mfma_f32_16x16x32_bf16 v[56:59], v[172:175], v[196:199], v[56:59]
	v_mfma_f32_16x16x32_bf16 v[52:55], v[176:179], v[192:195], v[52:55]
	v_mfma_f32_16x16x32_bf16 v[52:55], v[180:183], v[196:199], v[52:55]
	v_mfma_f32_16x16x32_bf16 v[36:39], v[176:179], v[200:203], v[36:39]
	v_mfma_f32_16x16x32_bf16 v[36:39], v[180:183], v[204:207], v[36:39]
	v_mfma_f32_16x16x32_bf16 v[20:23], v[176:179], v[208:211], v[20:23]
	v_mfma_f32_16x16x32_bf16 v[20:23], v[180:183], v[212:215], v[20:23]
	v_mfma_f32_16x16x32_bf16 v[4:7], v[176:179], v[216:219], v[4:7]
	v_mfma_f32_16x16x32_bf16 v[4:7], v[180:183], v[220:223], v[4:7]
	v_mfma_f32_16x16x32_bf16 v[0:3], v[184:187], v[216:219], v[0:3]
	v_mfma_f32_16x16x32_bf16 v[0:3], v[188:191], v[220:223], v[0:3]
	v_mfma_f32_16x16x32_bf16 v[16:19], v[184:187], v[208:211], v[16:19]
	v_mfma_f32_16x16x32_bf16 v[16:19], v[188:191], v[212:215], v[16:19]
	s_setprio 2
	s_barrier
; #define PG8_STAGE(bufoff, gbase, voff) do { _Pragma("unroll") for (int _i = 0; _i < 2; ++_i) \
;         __builtin_amdgcn_global_load_lds((const unsigned*)((const char*)(gbase) + (voff)[_i]), (PG8_LAS unsigned*)(lds + (bufoff) + ldsw + _i * 8192), 16, 0, 0); } while (0)
; #define PG8_LDA(dst, b, h) do { _Pragma("unroll") for (int m = 0; m < 4; ++m) _Pragma("unroll") for (int k = 0; k < 2; ++k) dst[m][k] = *(const PG8_LAS bf16x8*)(lds + PG8_SA(b, h) + aoff + m * 2048 + k * 1024); } while (0)
; #define PG8_LDB(dst, b, h) do { _Pragma("unroll") for (int n = 0; n < 2; ++n) _Pragma("unroll") for (int k = 0; k < 2; ++k) dst[n][k] = *(const PG8_LAS bf16x8*)(lds + PG8_SB(b, h) + boff + n * 2048 + k * 1024); } while (0)
; #define PG8_MMA(ai, bj, At, Bt) do { __builtin_amdgcn_s_setprio(1); _Pragma("unroll") for (int m = 0; m < 4; ++m) _Pragma("unroll") for (int n = 0; n < 2; ++n) _Pragma("unroll") for (int k = 0; k < 2; ++k) \
;         acc[ai][bj][m][n] = __builtin_amdgcn_mfma_f32_16x16x32_bf16(Bt[n][k], At[m][k], acc[ai][bj][m][n], 0, 0, 0); __builtin_amdgcn_s_setprio(0); } while (0)
; #define PG8_WAIT_V(n) asm volatile("s_waitcnt vmcnt(" #n ")" ::: "memory")
; #define PG8_WAIT_L(n) asm volatile("s_waitcnt lgkmcnt(" #n ")" ::: "memory")
; #define PG8_BAR __builtin_amdgcn_s_barrier()
; #define PG8_SCHED __builtin_amdgcn_sched_barrier(0)
; template <class Epi, class Sched, bool ALIGN_EPI = false, bool SP2 = false>
; __device__ __forceinline__ void gemm_phase(PG8_LAS unsigned char* lds, const Gemm g, const Sched& S, const Epi& E) {
;     ...
;             PG8_LDB(B0, 1, 0); PG8_LDB(B1, 1, 1); PG8_SCHED; PG8_LDA(At, 1, 0); PG8_STAGE(PG8_SA(0, 1), a2 + hstep, voffA);
;             PG8_WAIT_V(8); PG8_WAIT_L(0); PG8_BAR; PG8_MMA(0, 0, At, B0); PG8_MMA(0, 1, At, B1); PG8_BAR; PG8_SCHED;
	v_mfma_f32_16x16x32_bf16 v[32:35], v[184:187], v[200:203], v[32:35]
	v_mfma_f32_16x16x32_bf16 v[32:35], v[188:191], v[204:207], v[32:35]
	v_mfma_f32_16x16x32_bf16 v[48:51], v[184:187], v[192:195], v[48:51]
	v_mfma_f32_16x16x32_bf16 v[48:51], v[188:191], v[196:199], v[48:51]
	s_setprio 0
	s_add_i32 s62, 0, 0x18000
	s_add_i32 s63, 0, 0x1c000
	ds_read_b128 v[160:163], v155 offset:32768
	ds_read_b128 v[164:167], v155 offset:33792
	ds_read_b128 v[168:171], v155 offset:34816
	ds_read_b128 v[172:175], v155 offset:35840
	ds_read_b128 v[176:179], v157 offset:32768
	ds_read_b128 v[180:183], v157 offset:33792
	ds_read_b128 v[184:187], v157 offset:34816
	ds_read_b128 v[188:191], v157 offset:35840
	s_mov_b64 s[100:101], s[78:79]
	s_add_u32 s78, s78, 0x80000
	s_addc_u32 s79, s79, 0
	s_mov_b32 m0, s66
	ds_read_b128 v[192:195], v159 offset:32768
	ds_read_b128 v[196:199], v159 offset:33792
	ds_read_b128 v[200:203], v159 offset:34816
	ds_read_b128 v[204:207], v159 offset:35840
	ds_read_b128 v[208:211], v159 offset:36864
	ds_read_b128 v[212:215], v159 offset:37888
	ds_read_b128 v[216:219], v159 offset:38912
	ds_read_b128 v[220:223], v159 offset:39936
	global_load_lds_dwordx4 v128, s[78:79]
	s_mov_b32 m0, s67
	s_nop 0
	global_load_lds_dwordx4 v132, s[78:79]
	s_waitcnt vmcnt(8)
	s_waitcnt lgkmcnt(0)
	s_setprio 1
	s_barrier
	v_mfma_f32_16x16x32_bf16 v[124:127], v[160:163], v[192:195], v[124:127]
	v_mfma_f32_16x16x32_bf16 v[124:127], v[164:167], v[196:199], v[124:127]
	v_mfma_f32_16x16x32_bf16 v[108:111], v[160:163], v[200:203], v[108:111]
	v_mfma_f32_16x16x32_bf16 v[108:111], v[164:167], v[204:207], v[108:111]
	v_mfma_f32_16x16x32_bf16 v[92:95], v[160:163], v[208:211], v[92:95]
	v_mfma_f32_16x16x32_bf16 v[92:95], v[164:167], v[212:215], v[92:95]
	v_mfma_f32_16x16x32_bf16 v[76:79], v[160:163], v[216:219], v[76:79]
	v_mfma_f32_16x16x32_bf16 v[76:79], v[164:167], v[220:223], v[76:79]
	v_mfma_f32_16x16x32_bf16 v[72:75], v[168:171], v[216:219], v[72:75]
	v_mfma_f32_16x16x32_bf16 v[72:75], v[172:175], v[220:223], v[72:75]
	v_mfma_f32_16x16x32_bf16 v[88:91], v[168:171], v[208:211], v[88:91]
	v_mfma_f32_16x16x32_bf16 v[88:91], v[172:175], v[212:215], v[88:91]
	v_mfma_f32_16x16x32_bf16 v[104:107], v[168:171], v[200:203], v[104:107]
	v_mfma_f32_16x16x32_bf16 v[104:107], v[172:175], v[204:207], v[104:107]
	v_mfma_f32_16x16x32_bf16 v[120:123], v[168:171], v[192:195], v[120:123]
	v_mfma_f32_16x16x32_bf16 v[120:123], v[172:175], v[196:199], v[120:123]
	v_mfma_f32_16x16x32_bf16 v[116:119], v[176:179], v[192:195], v[116:119]
	v_mfma_f32_16x16x32_bf16 v[116:119], v[180:183], v[196:199], v[116:119]
	v_mfma_f32_16x16x32_bf16 v[100:103], v[176:179], v[200:203], v[100:103]
	v_mfma_f32_16x16x32_bf16 v[100:103], v[180:183], v[204:207], v[100:103]
	v_mfma_f32_16x16x32_bf16 v[84:87], v[176:179], v[208:211], v[84:87]
	v_mfma_f32_16x16x32_bf16 v[84:87], v[180:183], v[212:215], v[84:87]
	v_mfma_f32_16x16x32_bf16 v[68:71], v[176:179], v[216:219], v[68:71]
	v_mfma_f32_16x16x32_bf16 v[68:71], v[180:183], v[220:223], v[68:71]
	v_mfma_f32_16x16x32_bf16 v[64:67], v[184:187], v[216:219], v[64:67]
	v_mfma_f32_16x16x32_bf16 v[64:67], v[188:191], v[220:223], v[64:67]
	v_mfma_f32_16x16x32_bf16 v[80:83], v[184:187], v[208:211], v[80:83]
	v_mfma_f32_16x16x32_bf16 v[80:83], v[188:191], v[212:215], v[80:83]
	s_setprio 2
	s_barrier
; #define PG8_STAGE(bufoff, gbase, voff) do { _Pragma("unroll") for (int _i = 0; _i < 2; ++_i) \
;         __builtin_amdgcn_global_load_lds((const unsigned*)((const char*)(gbase) + (voff)[_i]), (PG8_LAS unsigned*)(lds + (bufoff) + ldsw + _i * 8192), 16, 0, 0); } while (0)
; #define PG8_LDA(dst, b, h) do { _Pragma("unroll") for (int m = 0; m < 4; ++m) _Pragma("unroll") for (int k = 0; k < 2; ++k) dst[m][k] = *(const PG8_LAS bf16x8*)(lds + PG8_SA(b, h) + aoff + m * 2048 + k * 1024); } while (0)
; #define PG8_MMA(ai, bj, At, Bt) do { __builtin_amdgcn_s_setprio(1); _Pragma("unroll") for (int m = 0; m < 4; ++m) _Pragma("unroll") for (int n = 0; n < 2; ++n) _Pragma("unroll") for (int k = 0; k < 2; ++k) \
;         acc[ai][bj][m][n] = __builtin_amdgcn_mfma_f32_16x16x32_bf16(Bt[n][k], At[m][k], acc[ai][bj][m][n], 0, 0, 0); __builtin_amdgcn_s_setprio(0); } while (0)
; #define PG8_WAIT_V(n) asm volatile("s_waitcnt vmcnt(" #n ")" ::: "memory")
; #define PG8_WAIT_L(n) asm volatile("s_waitcnt lgkmcnt(" #n ")" ::: "memory")
; #define PG8_BAR __builtin_amdgcn_s_barrier()
; #define PG8_SCHED __builtin_amdgcn_sched_barrier(0)
; template <class Epi, class Sched, bool ALIGN_EPI = false, bool SP2 = false>
; __device__ __forceinline__ void gemm_phase(PG8_LAS unsigned char* lds, const Gemm g, const Sched& S, const Epi& E) {
;     ...
;         for (int t = 0; t < nt; t += 2) {
;     ...
;             PG8_LDA(At, 1, 1); PG8_STAGE(PG8_SB(1, 0), b3, voffB); PG8_STAGE(PG8_SB(1, 1), b3 + hstep, voffB); PG8_STAGE(PG8_SA(1, 0), a3, voffA);
;             PG8_WAIT_V(8); PG8_WAIT_L(0); PG8_BAR; PG8_MMA(1, 0, At, B0); PG8_MMA(1, 1, At, B1); PG8_BAR; PG8_SCHED;
	v_mfma_f32_16x16x32_bf16 v[96:99], v[184:187], v[200:203], v[96:99]
	v_mfma_f32_16x16x32_bf16 v[96:99], v[188:191], v[204:207], v[96:99]
	v_mfma_f32_16x16x32_bf16 v[112:115], v[184:187], v[192:195], v[112:115]
	v_mfma_f32_16x16x32_bf16 v[112:115], v[188:191], v[196:199], v[112:115]
	s_setprio 0
	s_add_i32 s62, s62, s35
	s_add_i32 m0, s62, 0xffffff80
	ds_read_b128 v[192:195], v159 offset:49152
	ds_read_b128 v[196:199], v159 offset:50176
	ds_read_b128 v[200:203], v159 offset:51200
	ds_read_b128 v[204:207], v159 offset:52224
	ds_read_b128 v[208:211], v159 offset:53248
	ds_read_b128 v[212:215], v159 offset:54272
	ds_read_b128 v[216:219], v159 offset:55296
	ds_read_b128 v[220:223], v159 offset:56320
	global_load_lds_dwordx4 v130, s[76:77] offset:128
	s_add_i32 m0, s62, 0x1f80
	s_mov_b64 s[98:99], s[76:77]
	s_add_u32 s76, s76, 0x80080
	s_addc_u32 s77, s77, 0
	s_add_i32 s62, s63, s35
	global_load_lds_dwordx4 v134, s[98:99] offset:128
	s_mov_b32 m0, s62
	s_nop 0
	global_load_lds_dwordx4 v130, s[76:77]
	s_add_i32 m0, s62, 0x2000
	s_nop 0
	global_load_lds_dwordx4 v134, s[76:77]
	s_add_i32 m0, s81, 0xffffff80
	s_nop 0
	global_load_lds_dwordx4 v128, s[100:101] offset:128
	s_add_i32 m0, s82, 0xffffff80
	s_nop 0
	global_load_lds_dwordx4 v132, s[100:101] offset:128
	s_waitcnt vmcnt(8)
	s_waitcnt lgkmcnt(0)
	s_setprio 1
	s_barrier
	v_mfma_f32_16x16x32_bf16 v[60:63], v[160:163], v[192:195], v[60:63]
	v_mfma_f32_16x16x32_bf16 v[60:63], v[164:167], v[196:199], v[60:63]
	v_mfma_f32_16x16x32_bf16 v[44:47], v[160:163], v[200:203], v[44:47]
	v_mfma_f32_16x16x32_bf16 v[44:47], v[164:167], v[204:207], v[44:47]
	v_mfma_f32_16x16x32_bf16 v[28:31], v[160:163], v[208:211], v[28:31]
	v_mfma_f32_16x16x32_bf16 v[28:31], v[164:167], v[212:215], v[28:31]
	v_mfma_f32_16x16x32_bf16 v[12:15], v[160:163], v[216:219], v[12:15]
	v_mfma_f32_16x16x32_bf16 v[12:15], v[164:167], v[220:223], v[12:15]
	v_mfma_f32_16x16x32_bf16 v[8:11], v[168:171], v[216:219], v[8:11]
	v_mfma_f32_16x16x32_bf16 v[8:11], v[172:175], v[220:223], v[8:11]
	v_mfma_f32_16x16x32_bf16 v[24:27], v[168:171], v[208:211], v[24:27]
	v_mfma_f32_16x16x32_bf16 v[24:27], v[172:175], v[212:215], v[24:27]
	v_mfma_f32_16x16x32_bf16 v[40:43], v[168:171], v[200:203], v[40:43]
	v_mfma_f32_16x16x32_bf16 v[40:43], v[172:175], v[204:207], v[40:43]
	v_mfma_f32_16x16x32_bf16 v[56:59], v[168:171], v[192:195], v[56:59]
	v_mfma_f32_16x16x32_bf16 v[56:59], v[172:175], v[196:199], v[56:59]
	v_mfma_f32_16x16x32_bf16 v[52:55], v[176:179], v[192:195], v[52:55]
	v_mfma_f32_16x16x32_bf16 v[52:55], v[180:183], v[196:199], v[52:55]
	v_mfma_f32_16x16x32_bf16 v[36:39], v[176:179], v[200:203], v[36:39]
	v_mfma_f32_16x16x32_bf16 v[36:39], v[180:183], v[204:207], v[36:39]
	v_mfma_f32_16x16x32_bf16 v[20:23], v[176:179], v[208:211], v[20:23]
	v_mfma_f32_16x16x32_bf16 v[20:23], v[180:183], v[212:215], v[20:23]
	v_mfma_f32_16x16x32_bf16 v[4:7], v[176:179], v[216:219], v[4:7]
	v_mfma_f32_16x16x32_bf16 v[4:7], v[180:183], v[220:223], v[4:7]
	v_mfma_f32_16x16x32_bf16 v[0:3], v[184:187], v[216:219], v[0:3]
	v_mfma_f32_16x16x32_bf16 v[0:3], v[188:191], v[220:223], v[0:3]
	v_mfma_f32_16x16x32_bf16 v[16:19], v[184:187], v[208:211], v[16:19]
	v_mfma_f32_16x16x32_bf16 v[16:19], v[188:191], v[212:215], v[16:19]
	s_setprio 2
	s_barrier
	v_mfma_f32_16x16x32_bf16 v[32:35], v[184:187], v[200:203], v[32:35]
	v_mfma_f32_16x16x32_bf16 v[32:35], v[188:191], v[204:207], v[32:35]
	v_mfma_f32_16x16x32_bf16 v[48:51], v[184:187], v[192:195], v[48:51]
	v_mfma_f32_16x16x32_bf16 v[48:51], v[188:191], v[196:199], v[48:51]
	s_setprio 0
	s_add_i32 s90, s90, 2
	s_add_u32 s74, s74, 0x100
	s_addc_u32 s75, s75, 0
	s_add_u32 s88, s88, 0x100
	s_addc_u32 s89, s89, 0
	s_cmp_gt_u32 s90, 29
	s_cbranch_scc0 .LBB0_102
	s_and_b64 vcc, exec, s[22:23]
	s_cbranch_vccz .LBB0_105
	s_barrier

; #define PG8_STAGE(bufoff, gbase, voff) do { _Pragma("unroll") for (int _i = 0; _i < 2; ++_i) \
;         __builtin_amdgcn_global_load_lds((const unsigned*)((const char*)(gbase) + (voff)[_i]), (PG8_LAS unsigned*)(lds + (bufoff) + ldsw + _i * 8192), 16, 0, 0); } while (0)
; #define PG8_LDA(dst, b, h) do { _Pragma("unroll") for (int m = 0; m < 4; ++m) _Pragma("unroll") for (int k = 0; k < 2; ++k) dst[m][k] = *(const PG8_LAS bf16x8*)(lds + PG8_SA(b, h) + aoff + m * 2048 + k * 1024); } while (0)
; #define PG8_LDB(dst, b, h) do { _Pragma("unroll") for (int n = 0; n < 2; ++n) _Pragma("unroll") for (int k = 0; k < 2; ++k) dst[n][k] = *(const PG8_LAS bf16x8*)(lds + PG8_SB(b, h) + boff + n * 2048 + k * 1024); } while (0)
; #define PG8_MMA(ai, bj, At, Bt) do { __builtin_amdgcn_s_setprio(1); _Pragma("unroll") for (int m = 0; m < 4; ++m) _Pragma("unroll") for (int n = 0; n < 2; ++n) _Pragma("unroll") for (int k = 0; k < 2; ++k) \
;         acc[ai][bj][m][n] = __builtin_amdgcn_mfma_f32_16x16x32_bf16(Bt[n][k], At[m][k], acc[ai][bj][m][n], 0, 0, 0); __builtin_amdgcn_s_setprio(0); } while (0)
; #define PG8_WAIT_V(n) asm volatile("s_waitcnt vmcnt(" #n ")" ::: "memory")
; #define PG8_WAIT_L(n) asm volatile("s_waitcnt lgkmcnt(" #n ")" ::: "memory")
; template <class Epi, class Sched, bool ALIGN_EPI = false, bool SP2 = false>
; __device__ __forceinline__ void gemm_phase(PG8_LAS unsigned char* lds, const Gemm g, const Sched& S, const Epi& E) {
;     ...
;             const bool last = (t == nt - 2);
;             const char* a1 = cA + (size_t)(t + 1) * kstep;
;             const char* a2 = last ? nA : cA + (size_t)(t + 2) * kstep; const char* b2 = last ? nB : cB + (size_t)(t + 2) * kstep;
;             const char* a3 = a2 + kstep; const char* b3 = b2 + kstep;
;             if (last && has_next) S.a_ready(nxt);
;             if constexpr (SP2) {
;             PG8_LDB(B0, 0, 0); PG8_LDB(B1, 0, 1); PG8_SCHED; PG8_LDA(At, 0, 0); PG8_STAGE(PG8_SA(1, 1), a1 + hstep, voffA);
;             PG8_WAIT_V(8); PG8_WAIT_L(0); PG8_BAR; PG8_MMA(0, 0, At, B0); PG8_MMA(0, 1, At, B1); PG8_BAR; PG8_SCHED;
;             PG8_LDA(At, 0, 1); PG8_STAGE(PG8_SB(0, 0), b2, voffB); PG8_STAGE(PG8_SB(0, 1), b2 + hstep, voffB); PG8_STAGE(PG8_SA(0, 0), a2, voffA);
;             PG8_WAIT_V(8); PG8_WAIT_L(0); PG8_BAR; PG8_MMA(1, 0, At, B0); PG8_MMA(1, 1, At, B1); PG8_BAR; PG8_SCHED;
.LBB0_179:
	ds_read_b128 v[144:147], v155
	ds_read_b128 v[160:163], v155 offset:1024
	ds_read_b128 v[164:167], v155 offset:2048
	ds_read_b128 v[168:171], v155 offset:3072
	ds_read_b128 v[172:175], v156
	ds_read_b128 v[176:179], v156 offset:1024
	ds_read_b128 v[180:183], v156 offset:2048
	ds_read_b128 v[184:187], v156 offset:3072
	s_add_u32 s62, s76, 0xffea0080
	s_addc_u32 s63, s77, -1
	s_cmpk_eq_i32 s92, 0x54
	s_cselect_b32 s81, s7, s63
	s_cselect_b32 s80, s6, s62
	s_cselect_b32 s79, s75, s91
	s_cselect_b32 s78, s74, s50
	s_add_i32 m0, s52, 0xc000
	ds_read_b128 v[188:191], v157
	ds_read_b128 v[192:195], v157 offset:1024
	ds_read_b128 v[196:199], v157 offset:2048
	ds_read_b128 v[200:203], v157 offset:3072
	ds_read_b128 v[204:207], v157 offset:4096
	ds_read_b128 v[208:211], v157 offset:5120
	ds_read_b128 v[212:215], v157 offset:6144
	ds_read_b128 v[216:219], v157 offset:7168
	global_load_lds_dwordx4 v136, s[76:77]
	s_add_i32 m0, s52, 0xe000
	s_nop 0
	global_load_lds_dwordx4 v138, s[76:77]
	s_waitcnt vmcnt(8)
	s_waitcnt lgkmcnt(0)
	s_setprio 1
	s_barrier
	v_mfma_f32_16x16x32_bf16 v[124:127], v[144:147], v[188:191], v[124:127]
	v_mfma_f32_16x16x32_bf16 v[124:127], v[160:163], v[192:195], v[124:127]
	v_mfma_f32_16x16x32_bf16 v[108:111], v[144:147], v[196:199], v[108:111]
	v_mfma_f32_16x16x32_bf16 v[108:111], v[160:163], v[200:203], v[108:111]
	v_mfma_f32_16x16x32_bf16 v[92:95], v[144:147], v[204:207], v[92:95]
	v_mfma_f32_16x16x32_bf16 v[92:95], v[160:163], v[208:211], v[92:95]
	v_mfma_f32_16x16x32_bf16 v[76:79], v[144:147], v[212:215], v[76:79]
	v_mfma_f32_16x16x32_bf16 v[76:79], v[160:163], v[216:219], v[76:79]
	v_mfma_f32_16x16x32_bf16 v[72:75], v[164:167], v[212:215], v[72:75]
	v_mfma_f32_16x16x32_bf16 v[72:75], v[168:171], v[216:219], v[72:75]
	v_mfma_f32_16x16x32_bf16 v[88:91], v[164:167], v[204:207], v[88:91]
	v_mfma_f32_16x16x32_bf16 v[88:91], v[168:171], v[208:211], v[88:91]
	v_mfma_f32_16x16x32_bf16 v[104:107], v[164:167], v[196:199], v[104:107]
	v_mfma_f32_16x16x32_bf16 v[104:107], v[168:171], v[200:203], v[104:107]
	v_mfma_f32_16x16x32_bf16 v[120:123], v[164:167], v[188:191], v[120:123]
	v_mfma_f32_16x16x32_bf16 v[120:123], v[168:171], v[192:195], v[120:123]
	v_mfma_f32_16x16x32_bf16 v[116:119], v[172:175], v[188:191], v[116:119]
	v_mfma_f32_16x16x32_bf16 v[116:119], v[176:179], v[192:195], v[116:119]
	v_mfma_f32_16x16x32_bf16 v[100:103], v[172:175], v[196:199], v[100:103]
	v_mfma_f32_16x16x32_bf16 v[100:103], v[176:179], v[200:203], v[100:103]
	v_mfma_f32_16x16x32_bf16 v[84:87], v[172:175], v[204:207], v[84:87]
	v_mfma_f32_16x16x32_bf16 v[84:87], v[176:179], v[208:211], v[84:87]
	v_mfma_f32_16x16x32_bf16 v[68:71], v[172:175], v[212:215], v[68:71]
	v_mfma_f32_16x16x32_bf16 v[68:71], v[176:179], v[216:219], v[68:71]
	v_mfma_f32_16x16x32_bf16 v[64:67], v[180:183], v[212:215], v[64:67]
	v_mfma_f32_16x16x32_bf16 v[64:67], v[184:187], v[216:219], v[64:67]
	v_mfma_f32_16x16x32_bf16 v[80:83], v[180:183], v[204:207], v[80:83]
	v_mfma_f32_16x16x32_bf16 v[80:83], v[184:187], v[208:211], v[80:83]
	s_setprio 2
	s_barrier
	v_mfma_f32_16x16x32_bf16 v[96:99], v[180:183], v[196:199], v[96:99]
	v_mfma_f32_16x16x32_bf16 v[96:99], v[184:187], v[200:203], v[96:99]
	v_mfma_f32_16x16x32_bf16 v[112:115], v[180:183], v[188:191], v[112:115]
	v_mfma_f32_16x16x32_bf16 v[112:115], v[184:187], v[192:195], v[112:115]
	s_setprio 0
	s_add_i32 s62, s86, s35
	s_mov_b32 m0, s62
	ds_read_b128 v[188:191], v157 offset:16384
	ds_read_b128 v[192:195], v157 offset:17408
	ds_read_b128 v[196:199], v157 offset:18432
	ds_read_b128 v[200:203], v157 offset:19456
	ds_read_b128 v[204:207], v157 offset:20480
	ds_read_b128 v[208:211], v157 offset:21504
	ds_read_b128 v[212:215], v157 offset:22528
	ds_read_b128 v[216:219], v157 offset:23552
	global_load_lds_dwordx4 v130, s[78:79]
	s_add_i32 m0, s62, 0x2000
	s_add_u32 s94, s78, 0x160000
	s_addc_u32 s95, s79, 0
	s_add_i32 s62, s87, s35
	global_load_lds_dwordx4 v134, s[78:79]
	s_mov_b32 m0, s62
	s_nop 0
	global_load_lds_dwordx4 v130, s[94:95]
	s_add_i32 m0, s62, 0x2000
	s_nop 0
	global_load_lds_dwordx4 v134, s[94:95]
	s_mov_b32 m0, s52
	s_nop 0
	global_load_lds_dwordx4 v128, s[80:81]
	s_mov_b32 m0, s53
	s_nop 0
	global_load_lds_dwordx4 v132, s[80:81]
	s_waitcnt vmcnt(8)
	s_waitcnt lgkmcnt(0)
	s_setprio 1
	s_barrier
	v_mfma_f32_16x16x32_bf16 v[60:63], v[144:147], v[188:191], v[60:63]
	v_mfma_f32_16x16x32_bf16 v[60:63], v[160:163], v[192:195], v[60:63]
	v_mfma_f32_16x16x32_bf16 v[44:47], v[144:147], v[196:199], v[44:47]
	v_mfma_f32_16x16x32_bf16 v[44:47], v[160:163], v[200:203], v[44:47]
	v_mfma_f32_16x16x32_bf16 v[28:31], v[144:147], v[204:207], v[28:31]
	v_mfma_f32_16x16x32_bf16 v[28:31], v[160:163], v[208:211], v[28:31]
	v_mfma_f32_16x16x32_bf16 v[12:15], v[144:147], v[212:215], v[12:15]
	v_mfma_f32_16x16x32_bf16 v[12:15], v[160:163], v[216:219], v[12:15]
	v_mfma_f32_16x16x32_bf16 v[8:11], v[164:167], v[212:215], v[8:11]
	v_mfma_f32_16x16x32_bf16 v[8:11], v[168:171], v[216:219], v[8:11]
	v_mfma_f32_16x16x32_bf16 v[24:27], v[164:167], v[204:207], v[24:27]
	v_mfma_f32_16x16x32_bf16 v[24:27], v[168:171], v[208:211], v[24:27]
	v_mfma_f32_16x16x32_bf16 v[40:43], v[164:167], v[196:199], v[40:43]
	v_mfma_f32_16x16x32_bf16 v[40:43], v[168:171], v[200:203], v[40:43]
	v_mfma_f32_16x16x32_bf16 v[56:59], v[164:167], v[188:191], v[56:59]
	v_mfma_f32_16x16x32_bf16 v[56:59], v[168:171], v[192:195], v[56:59]
	v_mfma_f32_16x16x32_bf16 v[52:55], v[172:175], v[188:191], v[52:55]
	v_mfma_f32_16x16x32_bf16 v[52:55], v[176:179], v[192:195], v[52:55]
	v_mfma_f32_16x16x32_bf16 v[36:39], v[172:175], v[196:199], v[36:39]
	v_mfma_f32_16x16x32_bf16 v[36:39], v[176:179], v[200:203], v[36:39]
	v_mfma_f32_16x16x32_bf16 v[20:23], v[172:175], v[204:207], v[20:23]
	v_mfma_f32_16x16x32_bf16 v[20:23], v[176:179], v[208:211], v[20:23]
	v_mfma_f32_16x16x32_bf16 v[4:7], v[172:175], v[212:215], v[4:7]
	v_mfma_f32_16x16x32_bf16 v[4:7], v[176:179], v[216:219], v[4:7]
	v_mfma_f32_16x16x32_bf16 v[0:3], v[180:183], v[212:215], v[0:3]
	v_mfma_f32_16x16x32_bf16 v[0:3], v[184:187], v[216:219], v[0:3]
	v_mfma_f32_16x16x32_bf16 v[16:19], v[180:183], v[204:207], v[16:19]
	v_mfma_f32_16x16x32_bf16 v[16:19], v[184:187], v[208:211], v[16:19]
	s_setprio 2
	s_barrier
; #define PG8_STAGE(bufoff, gbase, voff) do { _Pragma("unroll") for (int _i = 0; _i < 2; ++_i) \
;         __builtin_amdgcn_global_load_lds((const unsigned*)((const char*)(gbase) + (voff)[_i]), (PG8_LAS unsigned*)(lds + (bufoff) + ldsw + _i * 8192), 16, 0, 0); } while (0)
; #define PG8_LDA(dst, b, h) do { _Pragma("unroll") for (int m = 0; m < 4; ++m) _Pragma("unroll") for (int k = 0; k < 2; ++k) dst[m][k] = *(const PG8_LAS bf16x8*)(lds + PG8_SA(b, h) + aoff + m * 2048 + k * 1024); } while (0)
; #define PG8_LDB(dst, b, h) do { _Pragma("unroll") for (int n = 0; n < 2; ++n) _Pragma("unroll") for (int k = 0; k < 2; ++k) dst[n][k] = *(const PG8_LAS bf16x8*)(lds + PG8_SB(b, h) + boff + n * 2048 + k * 1024); } while (0)
; #define PG8_MMA(ai, bj, At, Bt) do { __builtin_amdgcn_s_setprio(1); _Pragma("unroll") for (int m = 0; m < 4; ++m) _Pragma("unroll") for (int n = 0; n < 2; ++n) _Pragma("unroll") for (int k = 0; k < 2; ++k) \
;         acc[ai][bj][m][n] = __builtin_amdgcn_mfma_f32_16x16x32_bf16(Bt[n][k], At[m][k], acc[ai][bj][m][n], 0, 0, 0); __builtin_amdgcn_s_setprio(0); } while (0)
; #define PG8_WAIT_V(n) asm volatile("s_waitcnt vmcnt(" #n ")" ::: "memory")
; #define PG8_WAIT_L(n) asm volatile("s_waitcnt lgkmcnt(" #n ")" ::: "memory")
; #define PG8_BAR __builtin_amdgcn_s_barrier()
; #define PG8_SCHED __builtin_amdgcn_sched_barrier(0)
; template <class Epi, class Sched, bool ALIGN_EPI = false, bool SP2 = false>
; __device__ __forceinline__ void gemm_phase(PG8_LAS unsigned char* lds, const Gemm g, const Sched& S, const Epi& E) {
;     ...
;             PG8_LDB(B0, 1, 0); PG8_LDB(B1, 1, 1); PG8_SCHED; PG8_LDA(At, 1, 0); PG8_STAGE(PG8_SA(0, 1), a2 + hstep, voffA);
;             PG8_WAIT_V(8); PG8_WAIT_L(0); PG8_BAR; PG8_MMA(0, 0, At, B0); PG8_MMA(0, 1, At, B1); PG8_BAR; PG8_SCHED;
	v_mfma_f32_16x16x32_bf16 v[32:35], v[180:183], v[196:199], v[32:35]
	v_mfma_f32_16x16x32_bf16 v[32:35], v[184:187], v[200:203], v[32:35]
	v_mfma_f32_16x16x32_bf16 v[48:51], v[180:183], v[188:191], v[48:51]
	v_mfma_f32_16x16x32_bf16 v[48:51], v[184:187], v[192:195], v[48:51]
	s_setprio 0
	s_add_i32 s62, 0, 0x18000
	s_add_i32 s63, 0, 0x1c000
	ds_read_b128 v[144:147], v155 offset:32768
	ds_read_b128 v[160:163], v155 offset:33792
	ds_read_b128 v[164:167], v155 offset:34816
	ds_read_b128 v[168:171], v155 offset:35840
	ds_read_b128 v[172:175], v156 offset:32768
	ds_read_b128 v[176:179], v156 offset:33792
	ds_read_b128 v[180:183], v156 offset:34816
	ds_read_b128 v[184:187], v156 offset:35840
	s_mov_b64 s[100:101], s[80:81]
	s_add_u32 s80, s80, 0x160000
	s_addc_u32 s81, s81, 0
	s_mov_b32 m0, s61
	ds_read_b128 v[188:191], v157 offset:32768
	ds_read_b128 v[192:195], v157 offset:33792
	ds_read_b128 v[196:199], v157 offset:34816
	ds_read_b128 v[200:203], v157 offset:35840
	ds_read_b128 v[204:207], v157 offset:36864
	ds_read_b128 v[208:211], v157 offset:37888
	ds_read_b128 v[212:215], v157 offset:38912
	ds_read_b128 v[216:219], v157 offset:39936
	global_load_lds_dwordx4 v128, s[80:81]
	s_mov_b32 m0, s65
	s_nop 0
	global_load_lds_dwordx4 v132, s[80:81]
	s_waitcnt vmcnt(8)
	s_waitcnt lgkmcnt(0)
	s_setprio 1
	s_barrier
	v_mfma_f32_16x16x32_bf16 v[124:127], v[144:147], v[188:191], v[124:127]
	v_mfma_f32_16x16x32_bf16 v[124:127], v[160:163], v[192:195], v[124:127]
	v_mfma_f32_16x16x32_bf16 v[108:111], v[144:147], v[196:199], v[108:111]
	v_mfma_f32_16x16x32_bf16 v[108:111], v[160:163], v[200:203], v[108:111]
	v_mfma_f32_16x16x32_bf16 v[92:95], v[144:147], v[204:207], v[92:95]
	v_mfma_f32_16x16x32_bf16 v[92:95], v[160:163], v[208:211], v[92:95]
	v_mfma_f32_16x16x32_bf16 v[76:79], v[144:147], v[212:215], v[76:79]
	v_mfma_f32_16x16x32_bf16 v[76:79], v[160:163], v[216:219], v[76:79]
	v_mfma_f32_16x16x32_bf16 v[72:75], v[164:167], v[212:215], v[72:75]
	v_mfma_f32_16x16x32_bf16 v[72:75], v[168:171], v[216:219], v[72:75]
	v_mfma_f32_16x16x32_bf16 v[88:91], v[164:167], v[204:207], v[88:91]
	v_mfma_f32_16x16x32_bf16 v[88:91], v[168:171], v[208:211], v[88:91]
	v_mfma_f32_16x16x32_bf16 v[104:107], v[164:167], v[196:199], v[104:107]
	v_mfma_f32_16x16x32_bf16 v[104:107], v[168:171], v[200:203], v[104:107]
	v_mfma_f32_16x16x32_bf16 v[120:123], v[164:167], v[188:191], v[120:123]
	v_mfma_f32_16x16x32_bf16 v[120:123], v[168:171], v[192:195], v[120:123]
	v_mfma_f32_16x16x32_bf16 v[116:119], v[172:175], v[188:191], v[116:119]
	v_mfma_f32_16x16x32_bf16 v[116:119], v[176:179], v[192:195], v[116:119]
	v_mfma_f32_16x16x32_bf16 v[100:103], v[172:175], v[196:199], v[100:103]
	v_mfma_f32_16x16x32_bf16 v[100:103], v[176:179], v[200:203], v[100:103]
	v_mfma_f32_16x16x32_bf16 v[84:87], v[172:175], v[204:207], v[84:87]
	v_mfma_f32_16x16x32_bf16 v[84:87], v[176:179], v[208:211], v[84:87]
	v_mfma_f32_16x16x32_bf16 v[68:71], v[172:175], v[212:215], v[68:71]
	v_mfma_f32_16x16x32_bf16 v[68:71], v[176:179], v[216:219], v[68:71]
	v_mfma_f32_16x16x32_bf16 v[64:67], v[180:183], v[212:215], v[64:67]
	v_mfma_f32_16x16x32_bf16 v[64:67], v[184:187], v[216:219], v[64:67]
	v_mfma_f32_16x16x32_bf16 v[80:83], v[180:183], v[204:207], v[80:83]
	v_mfma_f32_16x16x32_bf16 v[80:83], v[184:187], v[208:211], v[80:83]
	s_setprio 2
	s_barrier
; #define PG8_STAGE(bufoff, gbase, voff) do { _Pragma("unroll") for (int _i = 0; _i < 2; ++_i) \
;         __builtin_amdgcn_global_load_lds((const unsigned*)((const char*)(gbase) + (voff)[_i]), (PG8_LAS unsigned*)(lds + (bufoff) + ldsw + _i * 8192), 16, 0, 0); } while (0)
; #define PG8_LDA(dst, b, h) do { _Pragma("unroll") for (int m = 0; m < 4; ++m) _Pragma("unroll") for (int k = 0; k < 2; ++k) dst[m][k] = *(const PG8_LAS bf16x8*)(lds + PG8_SA(b, h) + aoff + m * 2048 + k * 1024); } while (0)
; #define PG8_MMA(ai, bj, At, Bt) do { __builtin_amdgcn_s_setprio(1); _Pragma("unroll") for (int m = 0; m < 4; ++m) _Pragma("unroll") for (int n = 0; n < 2; ++n) _Pragma("unroll") for (int k = 0; k < 2; ++k) \
;         acc[ai][bj][m][n] = __builtin_amdgcn_mfma_f32_16x16x32_bf16(Bt[n][k], At[m][k], acc[ai][bj][m][n], 0, 0, 0); __builtin_amdgcn_s_setprio(0); } while (0)
; #define PG8_WAIT_V(n) asm volatile("s_waitcnt vmcnt(" #n ")" ::: "memory")
; #define PG8_WAIT_L(n) asm volatile("s_waitcnt lgkmcnt(" #n ")" ::: "memory")
; #define PG8_BAR __builtin_amdgcn_s_barrier()
; #define PG8_SCHED __builtin_amdgcn_sched_barrier(0)
; template <class Epi, class Sched, bool ALIGN_EPI = false, bool SP2 = false>
; __device__ __forceinline__ void gemm_phase(PG8_LAS unsigned char* lds, const Gemm g, const Sched& S, const Epi& E) {
;     ...
;         for (int t = 0; t < nt; t += 2) {
;     ...
;             PG8_LDA(At, 1, 1); PG8_STAGE(PG8_SB(1, 0), b3, voffB); PG8_STAGE(PG8_SB(1, 1), b3 + hstep, voffB); PG8_STAGE(PG8_SA(1, 0), a3, voffA);
;             PG8_WAIT_V(8); PG8_WAIT_L(0); PG8_BAR; PG8_MMA(1, 0, At, B0); PG8_MMA(1, 1, At, B1); PG8_BAR; PG8_SCHED;
	v_mfma_f32_16x16x32_bf16 v[96:99], v[180:183], v[196:199], v[96:99]
	v_mfma_f32_16x16x32_bf16 v[96:99], v[184:187], v[200:203], v[96:99]
	v_mfma_f32_16x16x32_bf16 v[112:115], v[180:183], v[188:191], v[112:115]
	v_mfma_f32_16x16x32_bf16 v[112:115], v[184:187], v[192:195], v[112:115]
	s_setprio 0
	s_add_i32 s62, s62, s35
	s_add_i32 m0, s62, 0xffffff80
	ds_read_b128 v[188:191], v157 offset:49152
	ds_read_b128 v[192:195], v157 offset:50176
	ds_read_b128 v[196:199], v157 offset:51200
	ds_read_b128 v[200:203], v157 offset:52224
	ds_read_b128 v[204:207], v157 offset:53248
	ds_read_b128 v[208:211], v157 offset:54272
	ds_read_b128 v[212:215], v157 offset:55296
	ds_read_b128 v[216:219], v157 offset:56320
	global_load_lds_dwordx4 v130, s[78:79] offset:128
	s_add_i32 m0, s62, 0x1f80
	s_mov_b64 s[98:99], s[78:79]
	s_add_u32 s78, s78, 0x160080
	s_addc_u32 s79, s79, 0
	s_add_i32 s62, s63, s35
	global_load_lds_dwordx4 v134, s[98:99] offset:128
	s_mov_b32 m0, s62
	s_nop 0
	global_load_lds_dwordx4 v130, s[78:79]
	s_add_i32 m0, s62, 0x2000
	s_nop 0
	global_load_lds_dwordx4 v134, s[78:79]
	s_add_i32 m0, s83, 0xffffff80
	s_nop 0
	global_load_lds_dwordx4 v128, s[100:101] offset:128
	s_add_i32 m0, s84, 0xffffff80
	s_nop 0
	global_load_lds_dwordx4 v132, s[100:101] offset:128
	s_waitcnt vmcnt(8)
	s_waitcnt lgkmcnt(0)
	s_setprio 1
	s_barrier
	v_mfma_f32_16x16x32_bf16 v[60:63], v[144:147], v[188:191], v[60:63]
	v_mfma_f32_16x16x32_bf16 v[60:63], v[160:163], v[192:195], v[60:63]
	v_mfma_f32_16x16x32_bf16 v[44:47], v[144:147], v[196:199], v[44:47]
	v_mfma_f32_16x16x32_bf16 v[44:47], v[160:163], v[200:203], v[44:47]
	v_mfma_f32_16x16x32_bf16 v[28:31], v[144:147], v[204:207], v[28:31]
	v_mfma_f32_16x16x32_bf16 v[28:31], v[160:163], v[208:211], v[28:31]
	v_mfma_f32_16x16x32_bf16 v[12:15], v[144:147], v[212:215], v[12:15]
	v_mfma_f32_16x16x32_bf16 v[12:15], v[160:163], v[216:219], v[12:15]
	v_mfma_f32_16x16x32_bf16 v[8:11], v[164:167], v[212:215], v[8:11]
	v_mfma_f32_16x16x32_bf16 v[8:11], v[168:171], v[216:219], v[8:11]
	v_mfma_f32_16x16x32_bf16 v[24:27], v[164:167], v[204:207], v[24:27]
	v_mfma_f32_16x16x32_bf16 v[24:27], v[168:171], v[208:211], v[24:27]
	v_mfma_f32_16x16x32_bf16 v[40:43], v[164:167], v[196:199], v[40:43]
	v_mfma_f32_16x16x32_bf16 v[40:43], v[168:171], v[200:203], v[40:43]
	v_mfma_f32_16x16x32_bf16 v[56:59], v[164:167], v[188:191], v[56:59]
	v_mfma_f32_16x16x32_bf16 v[56:59], v[168:171], v[192:195], v[56:59]
	v_mfma_f32_16x16x32_bf16 v[52:55], v[172:175], v[188:191], v[52:55]
	v_mfma_f32_16x16x32_bf16 v[52:55], v[176:179], v[192:195], v[52:55]
	v_mfma_f32_16x16x32_bf16 v[36:39], v[172:175], v[196:199], v[36:39]
	v_mfma_f32_16x16x32_bf16 v[36:39], v[176:179], v[200:203], v[36:39]
	v_mfma_f32_16x16x32_bf16 v[20:23], v[172:175], v[204:207], v[20:23]
	v_mfma_f32_16x16x32_bf16 v[20:23], v[176:179], v[208:211], v[20:23]
	v_mfma_f32_16x16x32_bf16 v[4:7], v[172:175], v[212:215], v[4:7]
	v_mfma_f32_16x16x32_bf16 v[4:7], v[176:179], v[216:219], v[4:7]
	v_mfma_f32_16x16x32_bf16 v[0:3], v[180:183], v[212:215], v[0:3]
	v_mfma_f32_16x16x32_bf16 v[0:3], v[184:187], v[216:219], v[0:3]
	v_mfma_f32_16x16x32_bf16 v[16:19], v[180:183], v[204:207], v[16:19]
	v_mfma_f32_16x16x32_bf16 v[16:19], v[184:187], v[208:211], v[16:19]
	s_setprio 2
	s_barrier
	v_mfma_f32_16x16x32_bf16 v[32:35], v[180:183], v[196:199], v[32:35]
	v_mfma_f32_16x16x32_bf16 v[32:35], v[184:187], v[200:203], v[32:35]
	v_mfma_f32_16x16x32_bf16 v[48:51], v[180:183], v[188:191], v[48:51]
	v_mfma_f32_16x16x32_bf16 v[48:51], v[184:187], v[192:195], v[48:51]
	s_setprio 0
	s_add_i32 s92, s92, 2
	s_add_u32 s76, s76, 0x100
	s_addc_u32 s77, s77, 0
	s_add_u32 s50, s50, 0x100
	s_addc_u32 s91, s91, 0
	s_cmpk_gt_u32 s92, 0x55
	s_cbranch_scc0 .LBB0_179
	s_and_b64 vcc, exec, s[58:59]
	s_cbranch_vccz .LBB0_182
	s_barrier

; #define PG8_STAGE(bufoff, gbase, voff) do { _Pragma("unroll") for (int _i = 0; _i < 2; ++_i) \
;         __builtin_amdgcn_global_load_lds((const unsigned*)((const char*)(gbase) + (voff)[_i]), (PG8_LAS unsigned*)(lds + (bufoff) + ldsw + _i * 8192), 16, 0, 0); } while (0)
; #define PG8_LDA(dst, b, h) do { _Pragma("unroll") for (int m = 0; m < 4; ++m) _Pragma("unroll") for (int k = 0; k < 2; ++k) dst[m][k] = *(const PG8_LAS bf16x8*)(lds + PG8_SA(b, h) + aoff + m * 2048 + k * 1024); } while (0)
; #define PG8_LDB(dst, b, h) do { _Pragma("unroll") for (int n = 0; n < 2; ++n) _Pragma("unroll") for (int k = 0; k < 2; ++k) dst[n][k] = *(const PG8_LAS bf16x8*)(lds + PG8_SB(b, h) + boff + n * 2048 + k * 1024); } while (0)
; #define PG8_MMA(ai, bj, At, Bt) do { __builtin_amdgcn_s_setprio(1); _Pragma("unroll") for (int m = 0; m < 4; ++m) _Pragma("unroll") for (int n = 0; n < 2; ++n) _Pragma("unroll") for (int k = 0; k < 2; ++k) \
;         acc[ai][bj][m][n] = __builtin_amdgcn_mfma_f32_16x16x32_bf16(Bt[n][k], At[m][k], acc[ai][bj][m][n], 0, 0, 0); __builtin_amdgcn_s_setprio(0); } while (0)
; #define PG8_WAIT_V(n) asm volatile("s_waitcnt vmcnt(" #n ")" ::: "memory")
; #define PG8_WAIT_L(n) asm volatile("s_waitcnt lgkmcnt(" #n ")" ::: "memory")
; template <class Epi, class Sched, bool ALIGN_EPI = false, bool SP2 = false>
; __device__ __forceinline__ void gemm_phase(PG8_LAS unsigned char* lds, const Gemm g, const Sched& S, const Epi& E) {
;     ...
;             const bool last = (t == nt - 2);
;             const char* a1 = cA + (size_t)(t + 1) * kstep;
;             const char* a2 = last ? nA : cA + (size_t)(t + 2) * kstep; const char* b2 = last ? nB : cB + (size_t)(t + 2) * kstep;
;             const char* a3 = a2 + kstep; const char* b3 = b2 + kstep;
;             if (last && has_next) S.a_ready(nxt);
;             if constexpr (SP2) {
;             PG8_LDB(B0, 0, 0); PG8_LDB(B1, 0, 1); PG8_SCHED; PG8_LDA(At, 0, 0); PG8_STAGE(PG8_SA(1, 1), a1 + hstep, voffA);
;             PG8_WAIT_V(8); PG8_WAIT_L(0); PG8_BAR; PG8_MMA(0, 0, At, B0); PG8_MMA(0, 1, At, B1); PG8_BAR; PG8_SCHED;
;             PG8_LDA(At, 0, 1); PG8_STAGE(PG8_SB(0, 0), b2, voffB); PG8_STAGE(PG8_SB(0, 1), b2 + hstep, voffB); PG8_STAGE(PG8_SA(0, 0), a2, voffA);
;             PG8_WAIT_V(8); PG8_WAIT_L(0); PG8_BAR; PG8_MMA(1, 0, At, B0); PG8_MMA(1, 1, At, B1); PG8_BAR; PG8_SCHED;
.LBB0_326:
	ds_read_b128 v[178:181], v176
	ds_read_b128 v[182:185], v176 offset:1024
	ds_read_b128 v[186:189], v176 offset:2048
	ds_read_b128 v[190:193], v176 offset:3072
	ds_read_b128 v[194:197], v177
	ds_read_b128 v[198:201], v177 offset:1024
	ds_read_b128 v[202:205], v177 offset:2048
	ds_read_b128 v[206:209], v177 offset:3072
	s_add_u32 s62, s76, 0xfff80080
	s_addc_u32 s63, s77, -1
	s_cmp_eq_u32 s75, 28
	s_cselect_b32 s81, s10, s63
	s_cselect_b32 s80, s11, s62
	s_cselect_b32 s79, s51, s67
	s_cselect_b32 s78, s55, s57
	s_add_i32 m0, s64, 0xc000
	ds_read_b128 v[210:213], v145
	ds_read_b128 v[214:217], v145 offset:1024
	ds_read_b128 v[218:221], v145 offset:2048
	ds_read_b128 v[222:225], v145 offset:3072
	ds_read_b128 v[226:229], v145 offset:4096
	ds_read_b128 v[230:233], v145 offset:5120
	ds_read_b128 v[234:237], v145 offset:6144
	ds_read_b128 v[238:241], v145 offset:7168
	global_load_lds_dwordx4 v146, s[76:77]
	s_add_i32 m0, s64, 0xe000
	s_nop 0
	global_load_lds_dwordx4 v152, s[76:77]
	s_waitcnt vmcnt(8)
	s_waitcnt lgkmcnt(0)
	s_setprio 1
	s_barrier
	v_mfma_f32_16x16x32_bf16 v[124:127], v[178:181], v[210:213], v[124:127]
	v_mfma_f32_16x16x32_bf16 v[124:127], v[182:185], v[214:217], v[124:127]
	v_mfma_f32_16x16x32_bf16 v[116:119], v[178:181], v[218:221], v[116:119]
	v_mfma_f32_16x16x32_bf16 v[116:119], v[182:185], v[222:225], v[116:119]
	v_mfma_f32_16x16x32_bf16 v[108:111], v[178:181], v[226:229], v[108:111]
	v_mfma_f32_16x16x32_bf16 v[108:111], v[182:185], v[230:233], v[108:111]
	v_mfma_f32_16x16x32_bf16 v[100:103], v[178:181], v[234:237], v[100:103]
	v_mfma_f32_16x16x32_bf16 v[100:103], v[182:185], v[238:241], v[100:103]
	v_mfma_f32_16x16x32_bf16 v[96:99], v[186:189], v[234:237], v[96:99]
	v_mfma_f32_16x16x32_bf16 v[96:99], v[190:193], v[238:241], v[96:99]
	v_mfma_f32_16x16x32_bf16 v[104:107], v[186:189], v[226:229], v[104:107]
	v_mfma_f32_16x16x32_bf16 v[104:107], v[190:193], v[230:233], v[104:107]
	v_mfma_f32_16x16x32_bf16 v[112:115], v[186:189], v[218:221], v[112:115]
	v_mfma_f32_16x16x32_bf16 v[112:115], v[190:193], v[222:225], v[112:115]
	v_mfma_f32_16x16x32_bf16 v[120:123], v[186:189], v[210:213], v[120:123]
	v_mfma_f32_16x16x32_bf16 v[120:123], v[190:193], v[214:217], v[120:123]
	v_mfma_f32_16x16x32_bf16 v[68:71], v[194:197], v[210:213], v[68:71]
	v_mfma_f32_16x16x32_bf16 v[68:71], v[198:201], v[214:217], v[68:71]
	v_mfma_f32_16x16x32_bf16 v[52:55], v[194:197], v[218:221], v[52:55]
	v_mfma_f32_16x16x32_bf16 v[52:55], v[198:201], v[222:225], v[52:55]
	v_mfma_f32_16x16x32_bf16 v[44:47], v[194:197], v[226:229], v[44:47]
	v_mfma_f32_16x16x32_bf16 v[44:47], v[198:201], v[230:233], v[44:47]
	v_mfma_f32_16x16x32_bf16 v[36:39], v[194:197], v[234:237], v[36:39]
	v_mfma_f32_16x16x32_bf16 v[36:39], v[198:201], v[238:241], v[36:39]
	v_mfma_f32_16x16x32_bf16 v[32:35], v[202:205], v[234:237], v[32:35]
	v_mfma_f32_16x16x32_bf16 v[32:35], v[206:209], v[238:241], v[32:35]
	v_mfma_f32_16x16x32_bf16 v[40:43], v[202:205], v[226:229], v[40:43]
	v_mfma_f32_16x16x32_bf16 v[40:43], v[206:209], v[230:233], v[40:43]
	s_setprio 2
	s_barrier
	v_mfma_f32_16x16x32_bf16 v[48:51], v[202:205], v[218:221], v[48:51]
	v_mfma_f32_16x16x32_bf16 v[48:51], v[206:209], v[222:225], v[48:51]
	v_mfma_f32_16x16x32_bf16 v[64:67], v[202:205], v[210:213], v[64:67]
	v_mfma_f32_16x16x32_bf16 v[64:67], v[206:209], v[214:217], v[64:67]
	s_setprio 0
	s_add_i32 s62, s53, s3
	s_mov_b32 m0, s62
	ds_read_b128 v[210:213], v145 offset:16384
	ds_read_b128 v[214:217], v145 offset:17408
	ds_read_b128 v[218:221], v145 offset:18432
	ds_read_b128 v[222:225], v145 offset:19456
	ds_read_b128 v[226:229], v145 offset:20480
	ds_read_b128 v[230:233], v145 offset:21504
	ds_read_b128 v[234:237], v145 offset:22528
	ds_read_b128 v[238:241], v145 offset:23552
	global_load_lds_dwordx4 v130, s[78:79]
	s_add_i32 m0, s62, 0x2000
	s_add_u32 s82, s78, 0x80000
	s_addc_u32 s83, s79, 0
	s_add_i32 s62, s66, s3
	global_load_lds_dwordx4 v134, s[78:79]
	s_mov_b32 m0, s62
	s_nop 0
	global_load_lds_dwordx4 v130, s[82:83]
	s_add_i32 m0, s62, 0x2000
	s_nop 0
	global_load_lds_dwordx4 v134, s[82:83]
	s_mov_b32 m0, s64
	s_nop 0
	global_load_lds_dwordx4 v128, s[80:81]
	s_mov_b32 m0, s65
	s_nop 0
	global_load_lds_dwordx4 v132, s[80:81]
	s_waitcnt vmcnt(8)
	s_waitcnt lgkmcnt(0)
	s_setprio 1
	s_barrier
	v_mfma_f32_16x16x32_bf16 v[92:95], v[178:181], v[210:213], v[92:95]
	v_mfma_f32_16x16x32_bf16 v[92:95], v[182:185], v[214:217], v[92:95]
	v_mfma_f32_16x16x32_bf16 v[84:87], v[178:181], v[218:221], v[84:87]
	v_mfma_f32_16x16x32_bf16 v[84:87], v[182:185], v[222:225], v[84:87]
	v_mfma_f32_16x16x32_bf16 v[76:79], v[178:181], v[226:229], v[76:79]
	v_mfma_f32_16x16x32_bf16 v[76:79], v[182:185], v[230:233], v[76:79]
	v_mfma_f32_16x16x32_bf16 v[60:63], v[178:181], v[234:237], v[60:63]
	v_mfma_f32_16x16x32_bf16 v[60:63], v[182:185], v[238:241], v[60:63]
	v_mfma_f32_16x16x32_bf16 v[56:59], v[186:189], v[234:237], v[56:59]
	v_mfma_f32_16x16x32_bf16 v[56:59], v[190:193], v[238:241], v[56:59]
	v_mfma_f32_16x16x32_bf16 v[72:75], v[186:189], v[226:229], v[72:75]
	v_mfma_f32_16x16x32_bf16 v[72:75], v[190:193], v[230:233], v[72:75]
	v_mfma_f32_16x16x32_bf16 v[80:83], v[186:189], v[218:221], v[80:83]
	v_mfma_f32_16x16x32_bf16 v[80:83], v[190:193], v[222:225], v[80:83]
	v_mfma_f32_16x16x32_bf16 v[88:91], v[186:189], v[210:213], v[88:91]
	v_mfma_f32_16x16x32_bf16 v[88:91], v[190:193], v[214:217], v[88:91]
	v_mfma_f32_16x16x32_bf16 v[28:31], v[194:197], v[210:213], v[28:31]
	v_mfma_f32_16x16x32_bf16 v[28:31], v[198:201], v[214:217], v[28:31]
	v_mfma_f32_16x16x32_bf16 v[20:23], v[194:197], v[218:221], v[20:23]
	v_mfma_f32_16x16x32_bf16 v[20:23], v[198:201], v[222:225], v[20:23]
	v_mfma_f32_16x16x32_bf16 v[12:15], v[194:197], v[226:229], v[12:15]
	v_mfma_f32_16x16x32_bf16 v[12:15], v[198:201], v[230:233], v[12:15]
	v_mfma_f32_16x16x32_bf16 v[4:7], v[194:197], v[234:237], v[4:7]
	v_mfma_f32_16x16x32_bf16 v[4:7], v[198:201], v[238:241], v[4:7]
	v_mfma_f32_16x16x32_bf16 v[0:3], v[202:205], v[234:237], v[0:3]
	v_mfma_f32_16x16x32_bf16 v[0:3], v[206:209], v[238:241], v[0:3]
	v_mfma_f32_16x16x32_bf16 v[8:11], v[202:205], v[226:229], v[8:11]
	v_mfma_f32_16x16x32_bf16 v[8:11], v[206:209], v[230:233], v[8:11]
	s_setprio 2
	s_barrier
; #define PG8_STAGE(bufoff, gbase, voff) do { _Pragma("unroll") for (int _i = 0; _i < 2; ++_i) \
;         __builtin_amdgcn_global_load_lds((const unsigned*)((const char*)(gbase) + (voff)[_i]), (PG8_LAS unsigned*)(lds + (bufoff) + ldsw + _i * 8192), 16, 0, 0); } while (0)
; #define PG8_LDA(dst, b, h) do { _Pragma("unroll") for (int m = 0; m < 4; ++m) _Pragma("unroll") for (int k = 0; k < 2; ++k) dst[m][k] = *(const PG8_LAS bf16x8*)(lds + PG8_SA(b, h) + aoff + m * 2048 + k * 1024); } while (0)
; #define PG8_LDB(dst, b, h) do { _Pragma("unroll") for (int n = 0; n < 2; ++n) _Pragma("unroll") for (int k = 0; k < 2; ++k) dst[n][k] = *(const PG8_LAS bf16x8*)(lds + PG8_SB(b, h) + boff + n * 2048 + k * 1024); } while (0)
; #define PG8_MMA(ai, bj, At, Bt) do { __builtin_amdgcn_s_setprio(1); _Pragma("unroll") for (int m = 0; m < 4; ++m) _Pragma("unroll") for (int n = 0; n < 2; ++n) _Pragma("unroll") for (int k = 0; k < 2; ++k) \
;         acc[ai][bj][m][n] = __builtin_amdgcn_mfma_f32_16x16x32_bf16(Bt[n][k], At[m][k], acc[ai][bj][m][n], 0, 0, 0); __builtin_amdgcn_s_setprio(0); } while (0)
; #define PG8_WAIT_V(n) asm volatile("s_waitcnt vmcnt(" #n ")" ::: "memory")
; #define PG8_WAIT_L(n) asm volatile("s_waitcnt lgkmcnt(" #n ")" ::: "memory")
; #define PG8_BAR __builtin_amdgcn_s_barrier()
; #define PG8_SCHED __builtin_amdgcn_sched_barrier(0)
; template <class Epi, class Sched, bool ALIGN_EPI = false, bool SP2 = false>
; __device__ __forceinline__ void gemm_phase(PG8_LAS unsigned char* lds, const Gemm g, const Sched& S, const Epi& E) {
;     ...
;             PG8_LDB(B0, 1, 0); PG8_LDB(B1, 1, 1); PG8_SCHED; PG8_LDA(At, 1, 0); PG8_STAGE(PG8_SA(0, 1), a2 + hstep, voffA);
;             PG8_WAIT_V(8); PG8_WAIT_L(0); PG8_BAR; PG8_MMA(0, 0, At, B0); PG8_MMA(0, 1, At, B1); PG8_BAR; PG8_SCHED;
	v_mfma_f32_16x16x32_bf16 v[16:19], v[202:205], v[218:221], v[16:19]
	v_mfma_f32_16x16x32_bf16 v[16:19], v[206:209], v[222:225], v[16:19]
	v_mfma_f32_16x16x32_bf16 v[24:27], v[202:205], v[210:213], v[24:27]
	v_mfma_f32_16x16x32_bf16 v[24:27], v[206:209], v[214:217], v[24:27]
	s_setprio 0
	s_add_i32 s62, 0, 0x18000
	s_add_i32 s63, 0, 0x1c000
	ds_read_b128 v[178:181], v176 offset:32768
	ds_read_b128 v[182:185], v176 offset:33792
	ds_read_b128 v[186:189], v176 offset:34816
	ds_read_b128 v[190:193], v176 offset:35840
	ds_read_b128 v[194:197], v177 offset:32768
	ds_read_b128 v[198:201], v177 offset:33792
	ds_read_b128 v[202:205], v177 offset:34816
	ds_read_b128 v[206:209], v177 offset:35840
	s_mov_b64 s[100:101], s[80:81]
	s_add_u32 s80, s80, 0x80000
	s_addc_u32 s81, s81, 0
	s_mov_b32 m0, s86
	ds_read_b128 v[210:213], v145 offset:32768
	ds_read_b128 v[214:217], v145 offset:33792
	ds_read_b128 v[218:221], v145 offset:34816
	ds_read_b128 v[222:225], v145 offset:35840
	ds_read_b128 v[226:229], v145 offset:36864
	ds_read_b128 v[230:233], v145 offset:37888
	ds_read_b128 v[234:237], v145 offset:38912
	ds_read_b128 v[238:241], v145 offset:39936
	global_load_lds_dwordx4 v128, s[80:81]
	s_mov_b32 m0, s87
	s_nop 0
	global_load_lds_dwordx4 v132, s[80:81]
	s_waitcnt vmcnt(8)
	s_waitcnt lgkmcnt(0)
	s_setprio 1
	s_barrier
	v_mfma_f32_16x16x32_bf16 v[124:127], v[178:181], v[210:213], v[124:127]
	v_mfma_f32_16x16x32_bf16 v[124:127], v[182:185], v[214:217], v[124:127]
	v_mfma_f32_16x16x32_bf16 v[116:119], v[178:181], v[218:221], v[116:119]
	v_mfma_f32_16x16x32_bf16 v[116:119], v[182:185], v[222:225], v[116:119]
	v_mfma_f32_16x16x32_bf16 v[108:111], v[178:181], v[226:229], v[108:111]
	v_mfma_f32_16x16x32_bf16 v[108:111], v[182:185], v[230:233], v[108:111]
	v_mfma_f32_16x16x32_bf16 v[100:103], v[178:181], v[234:237], v[100:103]
	v_mfma_f32_16x16x32_bf16 v[100:103], v[182:185], v[238:241], v[100:103]
	v_mfma_f32_16x16x32_bf16 v[96:99], v[186:189], v[234:237], v[96:99]
	v_mfma_f32_16x16x32_bf16 v[96:99], v[190:193], v[238:241], v[96:99]
	v_mfma_f32_16x16x32_bf16 v[104:107], v[186:189], v[226:229], v[104:107]
	v_mfma_f32_16x16x32_bf16 v[104:107], v[190:193], v[230:233], v[104:107]
	v_mfma_f32_16x16x32_bf16 v[112:115], v[186:189], v[218:221], v[112:115]
	v_mfma_f32_16x16x32_bf16 v[112:115], v[190:193], v[222:225], v[112:115]
	v_mfma_f32_16x16x32_bf16 v[120:123], v[186:189], v[210:213], v[120:123]
	v_mfma_f32_16x16x32_bf16 v[120:123], v[190:193], v[214:217], v[120:123]
	v_mfma_f32_16x16x32_bf16 v[68:71], v[194:197], v[210:213], v[68:71]
	v_mfma_f32_16x16x32_bf16 v[68:71], v[198:201], v[214:217], v[68:71]
	v_mfma_f32_16x16x32_bf16 v[52:55], v[194:197], v[218:221], v[52:55]
	v_mfma_f32_16x16x32_bf16 v[52:55], v[198:201], v[222:225], v[52:55]
	v_mfma_f32_16x16x32_bf16 v[44:47], v[194:197], v[226:229], v[44:47]
	v_mfma_f32_16x16x32_bf16 v[44:47], v[198:201], v[230:233], v[44:47]
	v_mfma_f32_16x16x32_bf16 v[36:39], v[194:197], v[234:237], v[36:39]
	v_mfma_f32_16x16x32_bf16 v[36:39], v[198:201], v[238:241], v[36:39]
	v_mfma_f32_16x16x32_bf16 v[32:35], v[202:205], v[234:237], v[32:35]
	v_mfma_f32_16x16x32_bf16 v[32:35], v[206:209], v[238:241], v[32:35]
	v_mfma_f32_16x16x32_bf16 v[40:43], v[202:205], v[226:229], v[40:43]
	v_mfma_f32_16x16x32_bf16 v[40:43], v[206:209], v[230:233], v[40:43]
	s_setprio 2
	s_barrier
; #define PG8_STAGE(bufoff, gbase, voff) do { _Pragma("unroll") for (int _i = 0; _i < 2; ++_i) \
;         __builtin_amdgcn_global_load_lds((const unsigned*)((const char*)(gbase) + (voff)[_i]), (PG8_LAS unsigned*)(lds + (bufoff) + ldsw + _i * 8192), 16, 0, 0); } while (0)
; #define PG8_LDA(dst, b, h) do { _Pragma("unroll") for (int m = 0; m < 4; ++m) _Pragma("unroll") for (int k = 0; k < 2; ++k) dst[m][k] = *(const PG8_LAS bf16x8*)(lds + PG8_SA(b, h) + aoff + m * 2048 + k * 1024); } while (0)
; #define PG8_MMA(ai, bj, At, Bt) do { __builtin_amdgcn_s_setprio(1); _Pragma("unroll") for (int m = 0; m < 4; ++m) _Pragma("unroll") for (int n = 0; n < 2; ++n) _Pragma("unroll") for (int k = 0; k < 2; ++k) \
;         acc[ai][bj][m][n] = __builtin_amdgcn_mfma_f32_16x16x32_bf16(Bt[n][k], At[m][k], acc[ai][bj][m][n], 0, 0, 0); __builtin_amdgcn_s_setprio(0); } while (0)
; #define PG8_WAIT_V(n) asm volatile("s_waitcnt vmcnt(" #n ")" ::: "memory")
; #define PG8_WAIT_L(n) asm volatile("s_waitcnt lgkmcnt(" #n ")" ::: "memory")
; #define PG8_BAR __builtin_amdgcn_s_barrier()
; #define PG8_SCHED __builtin_amdgcn_sched_barrier(0)
; template <class Epi, class Sched, bool ALIGN_EPI = false, bool SP2 = false>
; __device__ __forceinline__ void gemm_phase(PG8_LAS unsigned char* lds, const Gemm g, const Sched& S, const Epi& E) {
;     ...
;         for (int t = 0; t < nt; t += 2) {
;     ...
;             PG8_LDA(At, 1, 1); PG8_STAGE(PG8_SB(1, 0), b3, voffB); PG8_STAGE(PG8_SB(1, 1), b3 + hstep, voffB); PG8_STAGE(PG8_SA(1, 0), a3, voffA);
;             PG8_WAIT_V(8); PG8_WAIT_L(0); PG8_BAR; PG8_MMA(1, 0, At, B0); PG8_MMA(1, 1, At, B1); PG8_BAR; PG8_SCHED;
	v_mfma_f32_16x16x32_bf16 v[48:51], v[202:205], v[218:221], v[48:51]
	v_mfma_f32_16x16x32_bf16 v[48:51], v[206:209], v[222:225], v[48:51]
	v_mfma_f32_16x16x32_bf16 v[64:67], v[202:205], v[210:213], v[64:67]
	v_mfma_f32_16x16x32_bf16 v[64:67], v[206:209], v[214:217], v[64:67]
	s_setprio 0
	s_add_i32 s62, s62, s3
	s_add_i32 m0, s62, 0xffffff80
	ds_read_b128 v[210:213], v145 offset:49152
	ds_read_b128 v[214:217], v145 offset:50176
	ds_read_b128 v[218:221], v145 offset:51200
	ds_read_b128 v[222:225], v145 offset:52224
	ds_read_b128 v[226:229], v145 offset:53248
	ds_read_b128 v[230:233], v145 offset:54272
	ds_read_b128 v[234:237], v145 offset:55296
	ds_read_b128 v[238:241], v145 offset:56320
	global_load_lds_dwordx4 v130, s[78:79] offset:128
	s_add_i32 m0, s62, 0x1f80
	s_mov_b64 s[98:99], s[78:79]
	s_add_u32 s78, s78, 0x80080
	s_addc_u32 s79, s79, 0
	s_add_i32 s62, s63, s3
	global_load_lds_dwordx4 v134, s[98:99] offset:128
	s_mov_b32 m0, s62
	s_nop 0
	global_load_lds_dwordx4 v130, s[78:79]
	s_add_i32 m0, s62, 0x2000
	s_nop 0
	global_load_lds_dwordx4 v134, s[78:79]
	s_add_i32 m0, s89, 0xffffff80
	s_nop 0
	global_load_lds_dwordx4 v128, s[100:101] offset:128
	s_add_i32 m0, s90, 0xffffff80
	s_nop 0
	global_load_lds_dwordx4 v132, s[100:101] offset:128
	s_waitcnt vmcnt(8)
	s_waitcnt lgkmcnt(0)
	s_setprio 1
	s_barrier
	v_mfma_f32_16x16x32_bf16 v[92:95], v[178:181], v[210:213], v[92:95]
	v_mfma_f32_16x16x32_bf16 v[92:95], v[182:185], v[214:217], v[92:95]
	v_mfma_f32_16x16x32_bf16 v[84:87], v[178:181], v[218:221], v[84:87]
	v_mfma_f32_16x16x32_bf16 v[84:87], v[182:185], v[222:225], v[84:87]
	v_mfma_f32_16x16x32_bf16 v[76:79], v[178:181], v[226:229], v[76:79]
	v_mfma_f32_16x16x32_bf16 v[76:79], v[182:185], v[230:233], v[76:79]
	v_mfma_f32_16x16x32_bf16 v[60:63], v[178:181], v[234:237], v[60:63]
	v_mfma_f32_16x16x32_bf16 v[60:63], v[182:185], v[238:241], v[60:63]
	v_mfma_f32_16x16x32_bf16 v[56:59], v[186:189], v[234:237], v[56:59]
	v_mfma_f32_16x16x32_bf16 v[56:59], v[190:193], v[238:241], v[56:59]
	v_mfma_f32_16x16x32_bf16 v[72:75], v[186:189], v[226:229], v[72:75]
	v_mfma_f32_16x16x32_bf16 v[72:75], v[190:193], v[230:233], v[72:75]
	v_mfma_f32_16x16x32_bf16 v[80:83], v[186:189], v[218:221], v[80:83]
	v_mfma_f32_16x16x32_bf16 v[80:83], v[190:193], v[222:225], v[80:83]
	v_mfma_f32_16x16x32_bf16 v[88:91], v[186:189], v[210:213], v[88:91]
	v_mfma_f32_16x16x32_bf16 v[88:91], v[190:193], v[214:217], v[88:91]
	v_mfma_f32_16x16x32_bf16 v[28:31], v[194:197], v[210:213], v[28:31]
	v_mfma_f32_16x16x32_bf16 v[28:31], v[198:201], v[214:217], v[28:31]
	v_mfma_f32_16x16x32_bf16 v[20:23], v[194:197], v[218:221], v[20:23]
	v_mfma_f32_16x16x32_bf16 v[20:23], v[198:201], v[222:225], v[20:23]
	v_mfma_f32_16x16x32_bf16 v[12:15], v[194:197], v[226:229], v[12:15]
	v_mfma_f32_16x16x32_bf16 v[12:15], v[198:201], v[230:233], v[12:15]
	v_mfma_f32_16x16x32_bf16 v[4:7], v[194:197], v[234:237], v[4:7]
	v_mfma_f32_16x16x32_bf16 v[4:7], v[198:201], v[238:241], v[4:7]
	v_mfma_f32_16x16x32_bf16 v[0:3], v[202:205], v[234:237], v[0:3]
	v_mfma_f32_16x16x32_bf16 v[0:3], v[206:209], v[238:241], v[0:3]
	v_mfma_f32_16x16x32_bf16 v[8:11], v[202:205], v[226:229], v[8:11]
	v_mfma_f32_16x16x32_bf16 v[8:11], v[206:209], v[230:233], v[8:11]
	s_setprio 2
	s_barrier
	v_mfma_f32_16x16x32_bf16 v[16:19], v[202:205], v[218:221], v[16:19]
	v_mfma_f32_16x16x32_bf16 v[16:19], v[206:209], v[222:225], v[16:19]
	v_mfma_f32_16x16x32_bf16 v[24:27], v[202:205], v[210:213], v[24:27]
	v_mfma_f32_16x16x32_bf16 v[24:27], v[206:209], v[214:217], v[24:27]
	s_setprio 0
	s_add_i32 s75, s75, 2
	s_add_u32 s76, s76, 0x100
	s_addc_u32 s77, s77, 0
	s_add_u32 s57, s57, 0x100
	s_addc_u32 s67, s67, 0
	s_cmp_gt_u32 s75, 29
	s_cbranch_scc0 .LBB0_326
	s_and_b64 vcc, exec, s[20:21]
	s_cbranch_vccz .LBB0_329
	s_barrier

; #define PG8_STAGE(bufoff, gbase, voff) do { _Pragma("unroll") for (int _i = 0; _i < 2; ++_i) \
;         __builtin_amdgcn_global_load_lds((const unsigned*)((const char*)(gbase) + (voff)[_i]), (PG8_LAS unsigned*)(lds + (bufoff) + ldsw + _i * 8192), 16, 0, 0); } while (0)
; #define PG8_LDA(dst, b, h) do { _Pragma("unroll") for (int m = 0; m < 4; ++m) _Pragma("unroll") for (int k = 0; k < 2; ++k) dst[m][k] = *(const PG8_LAS bf16x8*)(lds + PG8_SA(b, h) + aoff + m * 2048 + k * 1024); } while (0)
; #define PG8_LDB(dst, b, h) do { _Pragma("unroll") for (int n = 0; n < 2; ++n) _Pragma("unroll") for (int k = 0; k < 2; ++k) dst[n][k] = *(const PG8_LAS bf16x8*)(lds + PG8_SB(b, h) + boff + n * 2048 + k * 1024); } while (0)
; #define PG8_MMA(ai, bj, At, Bt) do { __builtin_amdgcn_s_setprio(1); _Pragma("unroll") for (int m = 0; m < 4; ++m) _Pragma("unroll") for (int n = 0; n < 2; ++n) _Pragma("unroll") for (int k = 0; k < 2; ++k) \
;         acc[ai][bj][m][n] = __builtin_amdgcn_mfma_f32_16x16x32_bf16(Bt[n][k], At[m][k], acc[ai][bj][m][n], 0, 0, 0); __builtin_amdgcn_s_setprio(0); } while (0)
; #define PG8_WAIT_V(n) asm volatile("s_waitcnt vmcnt(" #n ")" ::: "memory")
; #define PG8_WAIT_L(n) asm volatile("s_waitcnt lgkmcnt(" #n ")" ::: "memory")
; template <class Epi, class Sched, bool ALIGN_EPI = false, bool SP2 = false>
; __device__ __forceinline__ void gemm_phase(PG8_LAS unsigned char* lds, const Gemm g, const Sched& S, const Epi& E) {
;     ...
;             const bool last = (t == nt - 2);
;             const char* a1 = cA + (size_t)(t + 1) * kstep;
;             const char* a2 = last ? nA : cA + (size_t)(t + 2) * kstep; const char* b2 = last ? nB : cB + (size_t)(t + 2) * kstep;
;             const char* a3 = a2 + kstep; const char* b3 = b2 + kstep;
;             if (last && has_next) S.a_ready(nxt);
;             if constexpr (SP2) {
;             PG8_LDB(B0, 0, 0); PG8_LDB(B1, 0, 1); PG8_SCHED; PG8_LDA(At, 0, 0); PG8_STAGE(PG8_SA(1, 1), a1 + hstep, voffA);
;             PG8_WAIT_V(8); PG8_WAIT_L(0); PG8_BAR; PG8_MMA(0, 0, At, B0); PG8_MMA(0, 1, At, B1); PG8_BAR; PG8_SCHED;
;             PG8_LDA(At, 0, 1); PG8_STAGE(PG8_SB(0, 0), b2, voffB); PG8_STAGE(PG8_SB(0, 1), b2 + hstep, voffB); PG8_STAGE(PG8_SA(0, 0), a2, voffA);
;             PG8_WAIT_V(8); PG8_WAIT_L(0); PG8_BAR; PG8_MMA(1, 0, At, B0); PG8_MMA(1, 1, At, B1); PG8_BAR; PG8_SCHED;
.LBB0_557:
	ds_read_b128 v[144:147], v155
	ds_read_b128 v[160:163], v155 offset:1024
	ds_read_b128 v[164:167], v155 offset:2048
	ds_read_b128 v[168:171], v155 offset:3072
	ds_read_b128 v[172:175], v156
	ds_read_b128 v[176:179], v156 offset:1024
	ds_read_b128 v[180:183], v156 offset:2048
	ds_read_b128 v[184:187], v156 offset:3072
	s_add_u32 s54, s50, 0xfff80080
	s_addc_u32 s55, s51, -1
	s_cmp_eq_u32 s73, 28
	s_cselect_b32 s57, s10, s55
	s_cselect_b32 s56, s11, s54
	s_cselect_b32 s55, s41, s72
	s_cselect_b32 s54, s43, s49
	s_add_i32 m0, s33, 0xc000
	ds_read_b128 v[188:191], v157
	ds_read_b128 v[192:195], v157 offset:1024
	ds_read_b128 v[196:199], v157 offset:2048
	ds_read_b128 v[200:203], v157 offset:3072
	ds_read_b128 v[204:207], v157 offset:4096
	ds_read_b128 v[208:211], v157 offset:5120
	ds_read_b128 v[212:215], v157 offset:6144
	ds_read_b128 v[216:219], v157 offset:7168
	global_load_lds_dwordx4 v136, s[50:51]
	s_add_i32 m0, s33, 0xe000
	s_nop 0
	global_load_lds_dwordx4 v138, s[50:51]
	s_waitcnt vmcnt(8)
	s_waitcnt lgkmcnt(0)
	s_setprio 1
	s_barrier
	v_mfma_f32_16x16x32_bf16 v[124:127], v[144:147], v[188:191], v[124:127]
	v_mfma_f32_16x16x32_bf16 v[124:127], v[160:163], v[192:195], v[124:127]
	v_mfma_f32_16x16x32_bf16 v[108:111], v[144:147], v[196:199], v[108:111]
	v_mfma_f32_16x16x32_bf16 v[108:111], v[160:163], v[200:203], v[108:111]
	v_mfma_f32_16x16x32_bf16 v[92:95], v[144:147], v[204:207], v[92:95]
	v_mfma_f32_16x16x32_bf16 v[92:95], v[160:163], v[208:211], v[92:95]
	v_mfma_f32_16x16x32_bf16 v[76:79], v[144:147], v[212:215], v[76:79]
	v_mfma_f32_16x16x32_bf16 v[76:79], v[160:163], v[216:219], v[76:79]
	v_mfma_f32_16x16x32_bf16 v[72:75], v[164:167], v[212:215], v[72:75]
	v_mfma_f32_16x16x32_bf16 v[72:75], v[168:171], v[216:219], v[72:75]
	v_mfma_f32_16x16x32_bf16 v[88:91], v[164:167], v[204:207], v[88:91]
	v_mfma_f32_16x16x32_bf16 v[88:91], v[168:171], v[208:211], v[88:91]
	v_mfma_f32_16x16x32_bf16 v[104:107], v[164:167], v[196:199], v[104:107]
	v_mfma_f32_16x16x32_bf16 v[104:107], v[168:171], v[200:203], v[104:107]
	v_mfma_f32_16x16x32_bf16 v[120:123], v[164:167], v[188:191], v[120:123]
	v_mfma_f32_16x16x32_bf16 v[120:123], v[168:171], v[192:195], v[120:123]
	v_mfma_f32_16x16x32_bf16 v[116:119], v[172:175], v[188:191], v[116:119]
	v_mfma_f32_16x16x32_bf16 v[116:119], v[176:179], v[192:195], v[116:119]
	v_mfma_f32_16x16x32_bf16 v[100:103], v[172:175], v[196:199], v[100:103]
	v_mfma_f32_16x16x32_bf16 v[100:103], v[176:179], v[200:203], v[100:103]
	v_mfma_f32_16x16x32_bf16 v[84:87], v[172:175], v[204:207], v[84:87]
	v_mfma_f32_16x16x32_bf16 v[84:87], v[176:179], v[208:211], v[84:87]
	v_mfma_f32_16x16x32_bf16 v[68:71], v[172:175], v[212:215], v[68:71]
	v_mfma_f32_16x16x32_bf16 v[68:71], v[176:179], v[216:219], v[68:71]
	v_mfma_f32_16x16x32_bf16 v[64:67], v[180:183], v[212:215], v[64:67]
	v_mfma_f32_16x16x32_bf16 v[64:67], v[184:187], v[216:219], v[64:67]
	v_mfma_f32_16x16x32_bf16 v[80:83], v[180:183], v[204:207], v[80:83]
	v_mfma_f32_16x16x32_bf16 v[80:83], v[184:187], v[208:211], v[80:83]
	s_setprio 2
	s_barrier
	v_mfma_f32_16x16x32_bf16 v[96:99], v[180:183], v[196:199], v[96:99]
	v_mfma_f32_16x16x32_bf16 v[96:99], v[184:187], v[200:203], v[96:99]
	v_mfma_f32_16x16x32_bf16 v[112:115], v[180:183], v[188:191], v[112:115]
	v_mfma_f32_16x16x32_bf16 v[112:115], v[184:187], v[192:195], v[112:115]
	s_setprio 0
	s_add_i32 s62, s67, s3
	s_mov_b32 m0, s62
	ds_read_b128 v[188:191], v157 offset:16384
	ds_read_b128 v[192:195], v157 offset:17408
	ds_read_b128 v[196:199], v157 offset:18432
	ds_read_b128 v[200:203], v157 offset:19456
	ds_read_b128 v[204:207], v157 offset:20480
	ds_read_b128 v[208:211], v157 offset:21504
	ds_read_b128 v[212:215], v157 offset:22528
	ds_read_b128 v[216:219], v157 offset:23552
	global_load_lds_dwordx4 v130, s[54:55]
	s_add_i32 m0, s62, 0x2000
	s_add_u32 s62, s54, 0x80000
	s_addc_u32 s63, s55, 0
	s_add_i32 s74, s70, s3
	global_load_lds_dwordx4 v134, s[54:55]
	s_mov_b32 m0, s74
	s_nop 0
	global_load_lds_dwordx4 v130, s[62:63]
	s_add_i32 m0, s74, 0x2000
	s_nop 0
	global_load_lds_dwordx4 v134, s[62:63]
	s_mov_b32 m0, s33
	s_nop 0
	global_load_lds_dwordx4 v128, s[56:57]
	s_mov_b32 m0, s35
	s_nop 0
	global_load_lds_dwordx4 v132, s[56:57]
	s_waitcnt vmcnt(8)
	s_waitcnt lgkmcnt(0)
	s_setprio 1
	s_barrier
	v_mfma_f32_16x16x32_bf16 v[60:63], v[144:147], v[188:191], v[60:63]
	v_mfma_f32_16x16x32_bf16 v[60:63], v[160:163], v[192:195], v[60:63]
	v_mfma_f32_16x16x32_bf16 v[44:47], v[144:147], v[196:199], v[44:47]
	v_mfma_f32_16x16x32_bf16 v[44:47], v[160:163], v[200:203], v[44:47]
	v_mfma_f32_16x16x32_bf16 v[28:31], v[144:147], v[204:207], v[28:31]
	v_mfma_f32_16x16x32_bf16 v[28:31], v[160:163], v[208:211], v[28:31]
	v_mfma_f32_16x16x32_bf16 v[12:15], v[144:147], v[212:215], v[12:15]
	v_mfma_f32_16x16x32_bf16 v[12:15], v[160:163], v[216:219], v[12:15]
	v_mfma_f32_16x16x32_bf16 v[8:11], v[164:167], v[212:215], v[8:11]
	v_mfma_f32_16x16x32_bf16 v[8:11], v[168:171], v[216:219], v[8:11]
	v_mfma_f32_16x16x32_bf16 v[24:27], v[164:167], v[204:207], v[24:27]
	v_mfma_f32_16x16x32_bf16 v[24:27], v[168:171], v[208:211], v[24:27]
	v_mfma_f32_16x16x32_bf16 v[40:43], v[164:167], v[196:199], v[40:43]
	v_mfma_f32_16x16x32_bf16 v[40:43], v[168:171], v[200:203], v[40:43]
	v_mfma_f32_16x16x32_bf16 v[56:59], v[164:167], v[188:191], v[56:59]
	v_mfma_f32_16x16x32_bf16 v[56:59], v[168:171], v[192:195], v[56:59]
	v_mfma_f32_16x16x32_bf16 v[52:55], v[172:175], v[188:191], v[52:55]
	v_mfma_f32_16x16x32_bf16 v[52:55], v[176:179], v[192:195], v[52:55]
	v_mfma_f32_16x16x32_bf16 v[36:39], v[172:175], v[196:199], v[36:39]
	v_mfma_f32_16x16x32_bf16 v[36:39], v[176:179], v[200:203], v[36:39]
	v_mfma_f32_16x16x32_bf16 v[20:23], v[172:175], v[204:207], v[20:23]
	v_mfma_f32_16x16x32_bf16 v[20:23], v[176:179], v[208:211], v[20:23]
	v_mfma_f32_16x16x32_bf16 v[4:7], v[172:175], v[212:215], v[4:7]
	v_mfma_f32_16x16x32_bf16 v[4:7], v[176:179], v[216:219], v[4:7]
	v_mfma_f32_16x16x32_bf16 v[0:3], v[180:183], v[212:215], v[0:3]
	v_mfma_f32_16x16x32_bf16 v[0:3], v[184:187], v[216:219], v[0:3]
	v_mfma_f32_16x16x32_bf16 v[16:19], v[180:183], v[204:207], v[16:19]
	v_mfma_f32_16x16x32_bf16 v[16:19], v[184:187], v[208:211], v[16:19]
	s_setprio 2
	s_barrier
; #define PG8_STAGE(bufoff, gbase, voff) do { _Pragma("unroll") for (int _i = 0; _i < 2; ++_i) \
;         __builtin_amdgcn_global_load_lds((const unsigned*)((const char*)(gbase) + (voff)[_i]), (PG8_LAS unsigned*)(lds + (bufoff) + ldsw + _i * 8192), 16, 0, 0); } while (0)
; #define PG8_LDA(dst, b, h) do { _Pragma("unroll") for (int m = 0; m < 4; ++m) _Pragma("unroll") for (int k = 0; k < 2; ++k) dst[m][k] = *(const PG8_LAS bf16x8*)(lds + PG8_SA(b, h) + aoff + m * 2048 + k * 1024); } while (0)
; #define PG8_LDB(dst, b, h) do { _Pragma("unroll") for (int n = 0; n < 2; ++n) _Pragma("unroll") for (int k = 0; k < 2; ++k) dst[n][k] = *(const PG8_LAS bf16x8*)(lds + PG8_SB(b, h) + boff + n * 2048 + k * 1024); } while (0)
; #define PG8_MMA(ai, bj, At, Bt) do { __builtin_amdgcn_s_setprio(1); _Pragma("unroll") for (int m = 0; m < 4; ++m) _Pragma("unroll") for (int n = 0; n < 2; ++n) _Pragma("unroll") for (int k = 0; k < 2; ++k) \
;         acc[ai][bj][m][n] = __builtin_amdgcn_mfma_f32_16x16x32_bf16(Bt[n][k], At[m][k], acc[ai][bj][m][n], 0, 0, 0); __builtin_amdgcn_s_setprio(0); } while (0)
; #define PG8_WAIT_V(n) asm volatile("s_waitcnt vmcnt(" #n ")" ::: "memory")
; #define PG8_WAIT_L(n) asm volatile("s_waitcnt lgkmcnt(" #n ")" ::: "memory")
; #define PG8_BAR __builtin_amdgcn_s_barrier()
; #define PG8_SCHED __builtin_amdgcn_sched_barrier(0)
; template <class Epi, class Sched, bool ALIGN_EPI = false, bool SP2 = false>
; __device__ __forceinline__ void gemm_phase(PG8_LAS unsigned char* lds, const Gemm g, const Sched& S, const Epi& E) {
;     ...
;             PG8_LDB(B0, 1, 0); PG8_LDB(B1, 1, 1); PG8_SCHED; PG8_LDA(At, 1, 0); PG8_STAGE(PG8_SA(0, 1), a2 + hstep, voffA);
;             PG8_WAIT_V(8); PG8_WAIT_L(0); PG8_BAR; PG8_MMA(0, 0, At, B0); PG8_MMA(0, 1, At, B1); PG8_BAR; PG8_SCHED;
	v_mfma_f32_16x16x32_bf16 v[32:35], v[180:183], v[196:199], v[32:35]
	v_mfma_f32_16x16x32_bf16 v[32:35], v[184:187], v[200:203], v[32:35]
	v_mfma_f32_16x16x32_bf16 v[48:51], v[180:183], v[188:191], v[48:51]
	v_mfma_f32_16x16x32_bf16 v[48:51], v[184:187], v[192:195], v[48:51]
	s_setprio 0
	s_add_i32 s62, 0, 0x18000
	s_add_i32 s63, 0, 0x1c000
	ds_read_b128 v[144:147], v155 offset:32768
	ds_read_b128 v[160:163], v155 offset:33792
	ds_read_b128 v[164:167], v155 offset:34816
	ds_read_b128 v[168:171], v155 offset:35840
	ds_read_b128 v[172:175], v156 offset:32768
	ds_read_b128 v[176:179], v156 offset:33792
	ds_read_b128 v[180:183], v156 offset:34816
	ds_read_b128 v[184:187], v156 offset:35840
	s_mov_b64 s[100:101], s[56:57]
	s_add_u32 s56, s56, 0x80000
	s_addc_u32 s57, s57, 0
	s_mov_b32 m0, s52
	ds_read_b128 v[188:191], v157 offset:32768
	ds_read_b128 v[192:195], v157 offset:33792
	ds_read_b128 v[196:199], v157 offset:34816
	ds_read_b128 v[200:203], v157 offset:35840
	ds_read_b128 v[204:207], v157 offset:36864
	ds_read_b128 v[208:211], v157 offset:37888
	ds_read_b128 v[212:215], v157 offset:38912
	ds_read_b128 v[216:219], v157 offset:39936
	global_load_lds_dwordx4 v128, s[56:57]
	s_mov_b32 m0, s53
	s_nop 0
	global_load_lds_dwordx4 v132, s[56:57]
	s_waitcnt vmcnt(8)
	s_waitcnt lgkmcnt(0)
	s_setprio 1
	s_barrier
	v_mfma_f32_16x16x32_bf16 v[124:127], v[144:147], v[188:191], v[124:127]
	v_mfma_f32_16x16x32_bf16 v[124:127], v[160:163], v[192:195], v[124:127]
	v_mfma_f32_16x16x32_bf16 v[108:111], v[144:147], v[196:199], v[108:111]
	v_mfma_f32_16x16x32_bf16 v[108:111], v[160:163], v[200:203], v[108:111]
	v_mfma_f32_16x16x32_bf16 v[92:95], v[144:147], v[204:207], v[92:95]
	v_mfma_f32_16x16x32_bf16 v[92:95], v[160:163], v[208:211], v[92:95]
	v_mfma_f32_16x16x32_bf16 v[76:79], v[144:147], v[212:215], v[76:79]
	v_mfma_f32_16x16x32_bf16 v[76:79], v[160:163], v[216:219], v[76:79]
	v_mfma_f32_16x16x32_bf16 v[72:75], v[164:167], v[212:215], v[72:75]
	v_mfma_f32_16x16x32_bf16 v[72:75], v[168:171], v[216:219], v[72:75]
	v_mfma_f32_16x16x32_bf16 v[88:91], v[164:167], v[204:207], v[88:91]
	v_mfma_f32_16x16x32_bf16 v[88:91], v[168:171], v[208:211], v[88:91]
	v_mfma_f32_16x16x32_bf16 v[104:107], v[164:167], v[196:199], v[104:107]
	v_mfma_f32_16x16x32_bf16 v[104:107], v[168:171], v[200:203], v[104:107]
	v_mfma_f32_16x16x32_bf16 v[120:123], v[164:167], v[188:191], v[120:123]
	v_mfma_f32_16x16x32_bf16 v[120:123], v[168:171], v[192:195], v[120:123]
	v_mfma_f32_16x16x32_bf16 v[116:119], v[172:175], v[188:191], v[116:119]
	v_mfma_f32_16x16x32_bf16 v[116:119], v[176:179], v[192:195], v[116:119]
	v_mfma_f32_16x16x32_bf16 v[100:103], v[172:175], v[196:199], v[100:103]
	v_mfma_f32_16x16x32_bf16 v[100:103], v[176:179], v[200:203], v[100:103]
	v_mfma_f32_16x16x32_bf16 v[84:87], v[172:175], v[204:207], v[84:87]
	v_mfma_f32_16x16x32_bf16 v[84:87], v[176:179], v[208:211], v[84:87]
	v_mfma_f32_16x16x32_bf16 v[68:71], v[172:175], v[212:215], v[68:71]
	v_mfma_f32_16x16x32_bf16 v[68:71], v[176:179], v[216:219], v[68:71]
	v_mfma_f32_16x16x32_bf16 v[64:67], v[180:183], v[212:215], v[64:67]
	v_mfma_f32_16x16x32_bf16 v[64:67], v[184:187], v[216:219], v[64:67]
	v_mfma_f32_16x16x32_bf16 v[80:83], v[180:183], v[204:207], v[80:83]
	v_mfma_f32_16x16x32_bf16 v[80:83], v[184:187], v[208:211], v[80:83]
	s_setprio 2
	s_barrier
; #define PG8_STAGE(bufoff, gbase, voff) do { _Pragma("unroll") for (int _i = 0; _i < 2; ++_i) \
;         __builtin_amdgcn_global_load_lds((const unsigned*)((const char*)(gbase) + (voff)[_i]), (PG8_LAS unsigned*)(lds + (bufoff) + ldsw + _i * 8192), 16, 0, 0); } while (0)
; #define PG8_LDA(dst, b, h) do { _Pragma("unroll") for (int m = 0; m < 4; ++m) _Pragma("unroll") for (int k = 0; k < 2; ++k) dst[m][k] = *(const PG8_LAS bf16x8*)(lds + PG8_SA(b, h) + aoff + m * 2048 + k * 1024); } while (0)
; #define PG8_MMA(ai, bj, At, Bt) do { __builtin_amdgcn_s_setprio(1); _Pragma("unroll") for (int m = 0; m < 4; ++m) _Pragma("unroll") for (int n = 0; n < 2; ++n) _Pragma("unroll") for (int k = 0; k < 2; ++k) \
;         acc[ai][bj][m][n] = __builtin_amdgcn_mfma_f32_16x16x32_bf16(Bt[n][k], At[m][k], acc[ai][bj][m][n], 0, 0, 0); __builtin_amdgcn_s_setprio(0); } while (0)
; #define PG8_WAIT_V(n) asm volatile("s_waitcnt vmcnt(" #n ")" ::: "memory")
; #define PG8_WAIT_L(n) asm volatile("s_waitcnt lgkmcnt(" #n ")" ::: "memory")
; #define PG8_BAR __builtin_amdgcn_s_barrier()
; #define PG8_SCHED __builtin_amdgcn_sched_barrier(0)
; template <class Epi, class Sched, bool ALIGN_EPI = false, bool SP2 = false>
; __device__ __forceinline__ void gemm_phase(PG8_LAS unsigned char* lds, const Gemm g, const Sched& S, const Epi& E) {
;     ...
;         for (int t = 0; t < nt; t += 2) {
;     ...
;             PG8_LDA(At, 1, 1); PG8_STAGE(PG8_SB(1, 0), b3, voffB); PG8_STAGE(PG8_SB(1, 1), b3 + hstep, voffB); PG8_STAGE(PG8_SA(1, 0), a3, voffA);
;             PG8_WAIT_V(8); PG8_WAIT_L(0); PG8_BAR; PG8_MMA(1, 0, At, B0); PG8_MMA(1, 1, At, B1); PG8_BAR; PG8_SCHED;
	v_mfma_f32_16x16x32_bf16 v[96:99], v[180:183], v[196:199], v[96:99]
	v_mfma_f32_16x16x32_bf16 v[96:99], v[184:187], v[200:203], v[96:99]
	v_mfma_f32_16x16x32_bf16 v[112:115], v[180:183], v[188:191], v[112:115]
	v_mfma_f32_16x16x32_bf16 v[112:115], v[184:187], v[192:195], v[112:115]
	s_setprio 0
	s_add_i32 s56, s62, s3
	s_add_i32 m0, s56, 0xffffff80
	ds_read_b128 v[188:191], v157 offset:49152
	ds_read_b128 v[192:195], v157 offset:50176
	ds_read_b128 v[196:199], v157 offset:51200
	ds_read_b128 v[200:203], v157 offset:52224
	ds_read_b128 v[204:207], v157 offset:53248
	ds_read_b128 v[208:211], v157 offset:54272
	ds_read_b128 v[212:215], v157 offset:55296
	ds_read_b128 v[216:219], v157 offset:56320
	global_load_lds_dwordx4 v130, s[54:55] offset:128
	s_add_i32 m0, s56, 0x1f80
	s_mov_b64 s[98:99], s[54:55]
	s_add_u32 s54, s54, 0x80080
	s_addc_u32 s55, s55, 0
	s_add_i32 s56, s63, s3
	global_load_lds_dwordx4 v134, s[98:99] offset:128
	s_mov_b32 m0, s56
	s_nop 0
	global_load_lds_dwordx4 v130, s[54:55]
	s_add_i32 m0, s56, 0x2000
	s_nop 0
	global_load_lds_dwordx4 v134, s[54:55]
	s_add_i32 m0, s64, 0xffffff80
	s_nop 0
	global_load_lds_dwordx4 v128, s[100:101] offset:128
	s_add_i32 m0, s65, 0xffffff80
	s_nop 0
	global_load_lds_dwordx4 v132, s[100:101] offset:128
	s_waitcnt vmcnt(8)
	s_waitcnt lgkmcnt(0)
	s_setprio 1
	s_barrier
	v_mfma_f32_16x16x32_bf16 v[60:63], v[144:147], v[188:191], v[60:63]
	v_mfma_f32_16x16x32_bf16 v[60:63], v[160:163], v[192:195], v[60:63]
	v_mfma_f32_16x16x32_bf16 v[44:47], v[144:147], v[196:199], v[44:47]
	v_mfma_f32_16x16x32_bf16 v[44:47], v[160:163], v[200:203], v[44:47]
	v_mfma_f32_16x16x32_bf16 v[28:31], v[144:147], v[204:207], v[28:31]
	v_mfma_f32_16x16x32_bf16 v[28:31], v[160:163], v[208:211], v[28:31]
	v_mfma_f32_16x16x32_bf16 v[12:15], v[144:147], v[212:215], v[12:15]
	v_mfma_f32_16x16x32_bf16 v[12:15], v[160:163], v[216:219], v[12:15]
	v_mfma_f32_16x16x32_bf16 v[8:11], v[164:167], v[212:215], v[8:11]
	v_mfma_f32_16x16x32_bf16 v[8:11], v[168:171], v[216:219], v[8:11]
	v_mfma_f32_16x16x32_bf16 v[24:27], v[164:167], v[204:207], v[24:27]
	v_mfma_f32_16x16x32_bf16 v[24:27], v[168:171], v[208:211], v[24:27]
	v_mfma_f32_16x16x32_bf16 v[40:43], v[164:167], v[196:199], v[40:43]
	v_mfma_f32_16x16x32_bf16 v[40:43], v[168:171], v[200:203], v[40:43]
	v_mfma_f32_16x16x32_bf16 v[56:59], v[164:167], v[188:191], v[56:59]
	v_mfma_f32_16x16x32_bf16 v[56:59], v[168:171], v[192:195], v[56:59]
	v_mfma_f32_16x16x32_bf16 v[52:55], v[172:175], v[188:191], v[52:55]
	v_mfma_f32_16x16x32_bf16 v[52:55], v[176:179], v[192:195], v[52:55]
	v_mfma_f32_16x16x32_bf16 v[36:39], v[172:175], v[196:199], v[36:39]
	v_mfma_f32_16x16x32_bf16 v[36:39], v[176:179], v[200:203], v[36:39]
	v_mfma_f32_16x16x32_bf16 v[20:23], v[172:175], v[204:207], v[20:23]
	v_mfma_f32_16x16x32_bf16 v[20:23], v[176:179], v[208:211], v[20:23]
	v_mfma_f32_16x16x32_bf16 v[4:7], v[172:175], v[212:215], v[4:7]
	v_mfma_f32_16x16x32_bf16 v[4:7], v[176:179], v[216:219], v[4:7]
	v_mfma_f32_16x16x32_bf16 v[0:3], v[180:183], v[212:215], v[0:3]
	v_mfma_f32_16x16x32_bf16 v[0:3], v[184:187], v[216:219], v[0:3]
	v_mfma_f32_16x16x32_bf16 v[16:19], v[180:183], v[204:207], v[16:19]
	v_mfma_f32_16x16x32_bf16 v[16:19], v[184:187], v[208:211], v[16:19]
	s_setprio 2
	s_barrier
	v_mfma_f32_16x16x32_bf16 v[32:35], v[180:183], v[196:199], v[32:35]
	v_mfma_f32_16x16x32_bf16 v[32:35], v[184:187], v[200:203], v[32:35]
	v_mfma_f32_16x16x32_bf16 v[48:51], v[180:183], v[188:191], v[48:51]
	v_mfma_f32_16x16x32_bf16 v[48:51], v[184:187], v[192:195], v[48:51]
	s_setprio 0
	s_add_i32 s73, s73, 2
	s_add_u32 s50, s50, 0x100
	s_addc_u32 s51, s51, 0
	s_add_u32 s49, s49, 0x100
	s_addc_u32 s72, s72, 0
	s_cmp_gt_u32 s73, 29
	s_cbranch_scc0 .LBB0_557
	s_and_b64 vcc, exec, s[38:39]
	s_cbranch_vccz .LBB0_560
	s_barrier

; #define PG8_STAGE(bufoff, gbase, voff) do { _Pragma("unroll") for (int _i = 0; _i < 2; ++_i) \
;         __builtin_amdgcn_global_load_lds((const unsigned*)((const char*)(gbase) + (voff)[_i]), (PG8_LAS unsigned*)(lds + (bufoff) + ldsw + _i * 8192), 16, 0, 0); } while (0)
; #define PG8_LDA(dst, b, h) do { _Pragma("unroll") for (int m = 0; m < 4; ++m) _Pragma("unroll") for (int k = 0; k < 2; ++k) dst[m][k] = *(const PG8_LAS bf16x8*)(lds + PG8_SA(b, h) + aoff + m * 2048 + k * 1024); } while (0)
; #define PG8_LDB(dst, b, h) do { _Pragma("unroll") for (int n = 0; n < 2; ++n) _Pragma("unroll") for (int k = 0; k < 2; ++k) dst[n][k] = *(const PG8_LAS bf16x8*)(lds + PG8_SB(b, h) + boff + n * 2048 + k * 1024); } while (0)
; #define PG8_MMA(ai, bj, At, Bt) do { __builtin_amdgcn_s_setprio(1); _Pragma("unroll") for (int m = 0; m < 4; ++m) _Pragma("unroll") for (int n = 0; n < 2; ++n) _Pragma("unroll") for (int k = 0; k < 2; ++k) \
;         acc[ai][bj][m][n] = __builtin_amdgcn_mfma_f32_16x16x32_bf16(Bt[n][k], At[m][k], acc[ai][bj][m][n], 0, 0, 0); __builtin_amdgcn_s_setprio(0); } while (0)
; #define PG8_WAIT_V(n) asm volatile("s_waitcnt vmcnt(" #n ")" ::: "memory")
; #define PG8_WAIT_L(n) asm volatile("s_waitcnt lgkmcnt(" #n ")" ::: "memory")
; template <class Epi, class Sched, bool ALIGN_EPI = false, bool SP2 = false>
; __device__ __forceinline__ void gemm_phase(PG8_LAS unsigned char* lds, const Gemm g, const Sched& S, const Epi& E) {
;     ...
;             const bool last = (t == nt - 2);
;             const char* a1 = cA + (size_t)(t + 1) * kstep;
;             const char* a2 = last ? nA : cA + (size_t)(t + 2) * kstep; const char* b2 = last ? nB : cB + (size_t)(t + 2) * kstep;
;             const char* a3 = a2 + kstep; const char* b3 = b2 + kstep;
;             if (last && has_next) S.a_ready(nxt);
;             if constexpr (SP2) {
;             PG8_LDB(B0, 0, 0); PG8_LDB(B1, 0, 1); PG8_SCHED; PG8_LDA(At, 0, 0); PG8_STAGE(PG8_SA(1, 1), a1 + hstep, voffA);
;             PG8_WAIT_V(8); PG8_WAIT_L(0); PG8_BAR; PG8_MMA(0, 0, At, B0); PG8_MMA(0, 1, At, B1); PG8_BAR; PG8_SCHED;
;             PG8_LDA(At, 0, 1); PG8_STAGE(PG8_SB(0, 0), b2, voffB); PG8_STAGE(PG8_SB(0, 1), b2 + hstep, voffB); PG8_STAGE(PG8_SA(0, 0), a2, voffA);
;             PG8_WAIT_V(8); PG8_WAIT_L(0); PG8_BAR; PG8_MMA(1, 0, At, B0); PG8_MMA(1, 1, At, B1); PG8_BAR; PG8_SCHED;
.LBB0_700:
	ds_read_b128 v[164:167], v155
	ds_read_b128 v[168:171], v155 offset:1024
	ds_read_b128 v[172:175], v155 offset:2048
	ds_read_b128 v[176:179], v155 offset:3072
	ds_read_b128 v[180:183], v157
	ds_read_b128 v[184:187], v157 offset:1024
	ds_read_b128 v[188:191], v157 offset:2048
	ds_read_b128 v[192:195], v157 offset:3072
	s_add_u32 s46, s44, 0xfff80080
	s_addc_u32 s47, s45, -1
	s_cmp_eq_u32 s67, 28
	s_cselect_b32 s49, s10, s47
	s_cselect_b32 s48, s11, s46
	s_cselect_b32 s47, s21, s66
	s_cselect_b32 s46, s37, s65
	s_add_i32 m0, s43, 0xc000
	ds_read_b128 v[196:199], v159
	ds_read_b128 v[200:203], v159 offset:1024
	ds_read_b128 v[204:207], v159 offset:2048
	ds_read_b128 v[208:211], v159 offset:3072
	ds_read_b128 v[212:215], v159 offset:4096
	ds_read_b128 v[216:219], v159 offset:5120
	ds_read_b128 v[220:223], v159 offset:6144
	ds_read_b128 v[224:227], v159 offset:7168
	global_load_lds_dwordx4 v138, s[44:45]
	s_add_i32 m0, s43, 0xe000
	s_nop 0
	global_load_lds_dwordx4 v140, s[44:45]
	s_waitcnt vmcnt(8)
	s_waitcnt lgkmcnt(0)
	s_setprio 1
	s_barrier
	v_mfma_f32_16x16x32_bf16 v[124:127], v[164:167], v[196:199], v[124:127]
	v_mfma_f32_16x16x32_bf16 v[124:127], v[168:171], v[200:203], v[124:127]
	v_mfma_f32_16x16x32_bf16 v[108:111], v[164:167], v[204:207], v[108:111]
	v_mfma_f32_16x16x32_bf16 v[108:111], v[168:171], v[208:211], v[108:111]
	v_mfma_f32_16x16x32_bf16 v[92:95], v[164:167], v[212:215], v[92:95]
	v_mfma_f32_16x16x32_bf16 v[92:95], v[168:171], v[216:219], v[92:95]
	v_mfma_f32_16x16x32_bf16 v[76:79], v[164:167], v[220:223], v[76:79]
	v_mfma_f32_16x16x32_bf16 v[76:79], v[168:171], v[224:227], v[76:79]
	v_mfma_f32_16x16x32_bf16 v[72:75], v[172:175], v[220:223], v[72:75]
	v_mfma_f32_16x16x32_bf16 v[72:75], v[176:179], v[224:227], v[72:75]
	v_mfma_f32_16x16x32_bf16 v[88:91], v[172:175], v[212:215], v[88:91]
	v_mfma_f32_16x16x32_bf16 v[88:91], v[176:179], v[216:219], v[88:91]
	v_mfma_f32_16x16x32_bf16 v[104:107], v[172:175], v[204:207], v[104:107]
	v_mfma_f32_16x16x32_bf16 v[104:107], v[176:179], v[208:211], v[104:107]
	v_mfma_f32_16x16x32_bf16 v[120:123], v[172:175], v[196:199], v[120:123]
	v_mfma_f32_16x16x32_bf16 v[120:123], v[176:179], v[200:203], v[120:123]
	v_mfma_f32_16x16x32_bf16 v[116:119], v[180:183], v[196:199], v[116:119]
	v_mfma_f32_16x16x32_bf16 v[116:119], v[184:187], v[200:203], v[116:119]
	v_mfma_f32_16x16x32_bf16 v[100:103], v[180:183], v[204:207], v[100:103]
	v_mfma_f32_16x16x32_bf16 v[100:103], v[184:187], v[208:211], v[100:103]
	v_mfma_f32_16x16x32_bf16 v[84:87], v[180:183], v[212:215], v[84:87]
	v_mfma_f32_16x16x32_bf16 v[84:87], v[184:187], v[216:219], v[84:87]
	v_mfma_f32_16x16x32_bf16 v[68:71], v[180:183], v[220:223], v[68:71]
	v_mfma_f32_16x16x32_bf16 v[68:71], v[184:187], v[224:227], v[68:71]
	v_mfma_f32_16x16x32_bf16 v[64:67], v[188:191], v[220:223], v[64:67]
	v_mfma_f32_16x16x32_bf16 v[64:67], v[192:195], v[224:227], v[64:67]
	v_mfma_f32_16x16x32_bf16 v[80:83], v[188:191], v[212:215], v[80:83]
	v_mfma_f32_16x16x32_bf16 v[80:83], v[192:195], v[216:219], v[80:83]
	s_setprio 2
	s_barrier
	v_mfma_f32_16x16x32_bf16 v[96:99], v[188:191], v[204:207], v[96:99]
	v_mfma_f32_16x16x32_bf16 v[96:99], v[192:195], v[208:211], v[96:99]
	v_mfma_f32_16x16x32_bf16 v[112:115], v[188:191], v[196:199], v[112:115]
	v_mfma_f32_16x16x32_bf16 v[112:115], v[192:195], v[200:203], v[112:115]
	s_setprio 0
	s_add_i32 s62, s58, s3
	s_mov_b32 m0, s62
	ds_read_b128 v[196:199], v159 offset:16384
	ds_read_b128 v[200:203], v159 offset:17408
	ds_read_b128 v[204:207], v159 offset:18432
	ds_read_b128 v[208:211], v159 offset:19456
	ds_read_b128 v[212:215], v159 offset:20480
	ds_read_b128 v[216:219], v159 offset:21504
	ds_read_b128 v[220:223], v159 offset:22528
	ds_read_b128 v[224:227], v159 offset:23552
	global_load_lds_dwordx4 v130, s[46:47]
	s_add_i32 m0, s62, 0x2000
	s_add_u32 s62, s46, 0x80000
	s_addc_u32 s63, s47, 0
	s_add_i32 s68, s59, s3
	global_load_lds_dwordx4 v134, s[46:47]
	s_mov_b32 m0, s68
	s_nop 0
	global_load_lds_dwordx4 v130, s[62:63]
	s_add_i32 m0, s68, 0x2000
	s_nop 0
	global_load_lds_dwordx4 v134, s[62:63]
	s_mov_b32 m0, s43
	s_nop 0
	global_load_lds_dwordx4 v128, s[48:49]
	s_mov_b32 m0, s50
	s_nop 0
	global_load_lds_dwordx4 v132, s[48:49]
	s_waitcnt vmcnt(8)
	s_waitcnt lgkmcnt(0)
	s_setprio 1
	s_barrier
	v_mfma_f32_16x16x32_bf16 v[60:63], v[164:167], v[196:199], v[60:63]
	v_mfma_f32_16x16x32_bf16 v[60:63], v[168:171], v[200:203], v[60:63]
	v_mfma_f32_16x16x32_bf16 v[44:47], v[164:167], v[204:207], v[44:47]
	v_mfma_f32_16x16x32_bf16 v[44:47], v[168:171], v[208:211], v[44:47]
	v_mfma_f32_16x16x32_bf16 v[28:31], v[164:167], v[212:215], v[28:31]
	v_mfma_f32_16x16x32_bf16 v[28:31], v[168:171], v[216:219], v[28:31]
	v_mfma_f32_16x16x32_bf16 v[12:15], v[164:167], v[220:223], v[12:15]
	v_mfma_f32_16x16x32_bf16 v[12:15], v[168:171], v[224:227], v[12:15]
	v_mfma_f32_16x16x32_bf16 v[8:11], v[172:175], v[220:223], v[8:11]
	v_mfma_f32_16x16x32_bf16 v[8:11], v[176:179], v[224:227], v[8:11]
	v_mfma_f32_16x16x32_bf16 v[24:27], v[172:175], v[212:215], v[24:27]
	v_mfma_f32_16x16x32_bf16 v[24:27], v[176:179], v[216:219], v[24:27]
	v_mfma_f32_16x16x32_bf16 v[40:43], v[172:175], v[204:207], v[40:43]
	v_mfma_f32_16x16x32_bf16 v[40:43], v[176:179], v[208:211], v[40:43]
	v_mfma_f32_16x16x32_bf16 v[56:59], v[172:175], v[196:199], v[56:59]
	v_mfma_f32_16x16x32_bf16 v[56:59], v[176:179], v[200:203], v[56:59]
	v_mfma_f32_16x16x32_bf16 v[52:55], v[180:183], v[196:199], v[52:55]
	v_mfma_f32_16x16x32_bf16 v[52:55], v[184:187], v[200:203], v[52:55]
	v_mfma_f32_16x16x32_bf16 v[36:39], v[180:183], v[204:207], v[36:39]
	v_mfma_f32_16x16x32_bf16 v[36:39], v[184:187], v[208:211], v[36:39]
	v_mfma_f32_16x16x32_bf16 v[20:23], v[180:183], v[212:215], v[20:23]
	v_mfma_f32_16x16x32_bf16 v[20:23], v[184:187], v[216:219], v[20:23]
	v_mfma_f32_16x16x32_bf16 v[4:7], v[180:183], v[220:223], v[4:7]
	v_mfma_f32_16x16x32_bf16 v[4:7], v[184:187], v[224:227], v[4:7]
	v_mfma_f32_16x16x32_bf16 v[0:3], v[188:191], v[220:223], v[0:3]
	v_mfma_f32_16x16x32_bf16 v[0:3], v[192:195], v[224:227], v[0:3]
	v_mfma_f32_16x16x32_bf16 v[16:19], v[188:191], v[212:215], v[16:19]
	v_mfma_f32_16x16x32_bf16 v[16:19], v[192:195], v[216:219], v[16:19]
	s_setprio 2
	s_barrier
; #define PG8_STAGE(bufoff, gbase, voff) do { _Pragma("unroll") for (int _i = 0; _i < 2; ++_i) \
;         __builtin_amdgcn_global_load_lds((const unsigned*)((const char*)(gbase) + (voff)[_i]), (PG8_LAS unsigned*)(lds + (bufoff) + ldsw + _i * 8192), 16, 0, 0); } while (0)
; #define PG8_LDA(dst, b, h) do { _Pragma("unroll") for (int m = 0; m < 4; ++m) _Pragma("unroll") for (int k = 0; k < 2; ++k) dst[m][k] = *(const PG8_LAS bf16x8*)(lds + PG8_SA(b, h) + aoff + m * 2048 + k * 1024); } while (0)
; #define PG8_LDB(dst, b, h) do { _Pragma("unroll") for (int n = 0; n < 2; ++n) _Pragma("unroll") for (int k = 0; k < 2; ++k) dst[n][k] = *(const PG8_LAS bf16x8*)(lds + PG8_SB(b, h) + boff + n * 2048 + k * 1024); } while (0)
; #define PG8_MMA(ai, bj, At, Bt) do { __builtin_amdgcn_s_setprio(1); _Pragma("unroll") for (int m = 0; m < 4; ++m) _Pragma("unroll") for (int n = 0; n < 2; ++n) _Pragma("unroll") for (int k = 0; k < 2; ++k) \
;         acc[ai][bj][m][n] = __builtin_amdgcn_mfma_f32_16x16x32_bf16(Bt[n][k], At[m][k], acc[ai][bj][m][n], 0, 0, 0); __builtin_amdgcn_s_setprio(0); } while (0)
; #define PG8_WAIT_V(n) asm volatile("s_waitcnt vmcnt(" #n ")" ::: "memory")
; #define PG8_WAIT_L(n) asm volatile("s_waitcnt lgkmcnt(" #n ")" ::: "memory")
; #define PG8_BAR __builtin_amdgcn_s_barrier()
; #define PG8_SCHED __builtin_amdgcn_sched_barrier(0)
; template <class Epi, class Sched, bool ALIGN_EPI = false, bool SP2 = false>
; __device__ __forceinline__ void gemm_phase(PG8_LAS unsigned char* lds, const Gemm g, const Sched& S, const Epi& E) {
;     ...
;             PG8_LDB(B0, 1, 0); PG8_LDB(B1, 1, 1); PG8_SCHED; PG8_LDA(At, 1, 0); PG8_STAGE(PG8_SA(0, 1), a2 + hstep, voffA);
;             PG8_WAIT_V(8); PG8_WAIT_L(0); PG8_BAR; PG8_MMA(0, 0, At, B0); PG8_MMA(0, 1, At, B1); PG8_BAR; PG8_SCHED;
	v_mfma_f32_16x16x32_bf16 v[32:35], v[188:191], v[204:207], v[32:35]
	v_mfma_f32_16x16x32_bf16 v[32:35], v[192:195], v[208:211], v[32:35]
	v_mfma_f32_16x16x32_bf16 v[48:51], v[188:191], v[196:199], v[48:51]
	v_mfma_f32_16x16x32_bf16 v[48:51], v[192:195], v[200:203], v[48:51]
	s_setprio 0
	s_add_i32 s62, 0, 0x18000
	s_add_i32 s63, 0, 0x1c000
	ds_read_b128 v[164:167], v155 offset:32768
	ds_read_b128 v[168:171], v155 offset:33792
	ds_read_b128 v[172:175], v155 offset:34816
	ds_read_b128 v[176:179], v155 offset:35840
	ds_read_b128 v[180:183], v157 offset:32768
	ds_read_b128 v[184:187], v157 offset:33792
	ds_read_b128 v[188:191], v157 offset:34816
	ds_read_b128 v[192:195], v157 offset:35840
	s_mov_b64 s[100:101], s[48:49]
	s_add_u32 s48, s48, 0x80000
	s_addc_u32 s49, s49, 0
	s_mov_b32 m0, s51
	ds_read_b128 v[196:199], v159 offset:32768
	ds_read_b128 v[200:203], v159 offset:33792
	ds_read_b128 v[204:207], v159 offset:34816
	ds_read_b128 v[208:211], v159 offset:35840
	ds_read_b128 v[212:215], v159 offset:36864
	ds_read_b128 v[216:219], v159 offset:37888
	ds_read_b128 v[220:223], v159 offset:38912
	ds_read_b128 v[224:227], v159 offset:39936
	global_load_lds_dwordx4 v128, s[48:49]
	s_mov_b32 m0, s52
	s_nop 0
	global_load_lds_dwordx4 v132, s[48:49]
	s_waitcnt vmcnt(8)
	s_waitcnt lgkmcnt(0)
	s_setprio 1
	s_barrier
	v_mfma_f32_16x16x32_bf16 v[124:127], v[164:167], v[196:199], v[124:127]
	v_mfma_f32_16x16x32_bf16 v[124:127], v[168:171], v[200:203], v[124:127]
	v_mfma_f32_16x16x32_bf16 v[108:111], v[164:167], v[204:207], v[108:111]
	v_mfma_f32_16x16x32_bf16 v[108:111], v[168:171], v[208:211], v[108:111]
	v_mfma_f32_16x16x32_bf16 v[92:95], v[164:167], v[212:215], v[92:95]
	v_mfma_f32_16x16x32_bf16 v[92:95], v[168:171], v[216:219], v[92:95]
	v_mfma_f32_16x16x32_bf16 v[76:79], v[164:167], v[220:223], v[76:79]
	v_mfma_f32_16x16x32_bf16 v[76:79], v[168:171], v[224:227], v[76:79]
	v_mfma_f32_16x16x32_bf16 v[72:75], v[172:175], v[220:223], v[72:75]
	v_mfma_f32_16x16x32_bf16 v[72:75], v[176:179], v[224:227], v[72:75]
	v_mfma_f32_16x16x32_bf16 v[88:91], v[172:175], v[212:215], v[88:91]
	v_mfma_f32_16x16x32_bf16 v[88:91], v[176:179], v[216:219], v[88:91]
	v_mfma_f32_16x16x32_bf16 v[104:107], v[172:175], v[204:207], v[104:107]
	v_mfma_f32_16x16x32_bf16 v[104:107], v[176:179], v[208:211], v[104:107]
	v_mfma_f32_16x16x32_bf16 v[120:123], v[172:175], v[196:199], v[120:123]
	v_mfma_f32_16x16x32_bf16 v[120:123], v[176:179], v[200:203], v[120:123]
	v_mfma_f32_16x16x32_bf16 v[116:119], v[180:183], v[196:199], v[116:119]
	v_mfma_f32_16x16x32_bf16 v[116:119], v[184:187], v[200:203], v[116:119]
	v_mfma_f32_16x16x32_bf16 v[100:103], v[180:183], v[204:207], v[100:103]
	v_mfma_f32_16x16x32_bf16 v[100:103], v[184:187], v[208:211], v[100:103]
	v_mfma_f32_16x16x32_bf16 v[84:87], v[180:183], v[212:215], v[84:87]
	v_mfma_f32_16x16x32_bf16 v[84:87], v[184:187], v[216:219], v[84:87]
	v_mfma_f32_16x16x32_bf16 v[68:71], v[180:183], v[220:223], v[68:71]
	v_mfma_f32_16x16x32_bf16 v[68:71], v[184:187], v[224:227], v[68:71]
	v_mfma_f32_16x16x32_bf16 v[64:67], v[188:191], v[220:223], v[64:67]
	v_mfma_f32_16x16x32_bf16 v[64:67], v[192:195], v[224:227], v[64:67]
	v_mfma_f32_16x16x32_bf16 v[80:83], v[188:191], v[212:215], v[80:83]
	v_mfma_f32_16x16x32_bf16 v[80:83], v[192:195], v[216:219], v[80:83]
	s_setprio 2
	s_barrier
; #define PG8_STAGE(bufoff, gbase, voff) do { _Pragma("unroll") for (int _i = 0; _i < 2; ++_i) \
;         __builtin_amdgcn_global_load_lds((const unsigned*)((const char*)(gbase) + (voff)[_i]), (PG8_LAS unsigned*)(lds + (bufoff) + ldsw + _i * 8192), 16, 0, 0); } while (0)
; #define PG8_LDA(dst, b, h) do { _Pragma("unroll") for (int m = 0; m < 4; ++m) _Pragma("unroll") for (int k = 0; k < 2; ++k) dst[m][k] = *(const PG8_LAS bf16x8*)(lds + PG8_SA(b, h) + aoff + m * 2048 + k * 1024); } while (0)
; #define PG8_MMA(ai, bj, At, Bt) do { __builtin_amdgcn_s_setprio(1); _Pragma("unroll") for (int m = 0; m < 4; ++m) _Pragma("unroll") for (int n = 0; n < 2; ++n) _Pragma("unroll") for (int k = 0; k < 2; ++k) \
;         acc[ai][bj][m][n] = __builtin_amdgcn_mfma_f32_16x16x32_bf16(Bt[n][k], At[m][k], acc[ai][bj][m][n], 0, 0, 0); __builtin_amdgcn_s_setprio(0); } while (0)
; #define PG8_WAIT_V(n) asm volatile("s_waitcnt vmcnt(" #n ")" ::: "memory")
; #define PG8_WAIT_L(n) asm volatile("s_waitcnt lgkmcnt(" #n ")" ::: "memory")
; #define PG8_BAR __builtin_amdgcn_s_barrier()
; #define PG8_SCHED __builtin_amdgcn_sched_barrier(0)
; template <class Epi, class Sched, bool ALIGN_EPI = false, bool SP2 = false>
; __device__ __forceinline__ void gemm_phase(PG8_LAS unsigned char* lds, const Gemm g, const Sched& S, const Epi& E) {
;     ...
;         for (int t = 0; t < nt; t += 2) {
;     ...
;             PG8_LDA(At, 1, 1); PG8_STAGE(PG8_SB(1, 0), b3, voffB); PG8_STAGE(PG8_SB(1, 1), b3 + hstep, voffB); PG8_STAGE(PG8_SA(1, 0), a3, voffA);
;             PG8_WAIT_V(8); PG8_WAIT_L(0); PG8_BAR; PG8_MMA(1, 0, At, B0); PG8_MMA(1, 1, At, B1); PG8_BAR; PG8_SCHED;
	v_mfma_f32_16x16x32_bf16 v[96:99], v[188:191], v[204:207], v[96:99]
	v_mfma_f32_16x16x32_bf16 v[96:99], v[192:195], v[208:211], v[96:99]
	v_mfma_f32_16x16x32_bf16 v[112:115], v[188:191], v[196:199], v[112:115]
	v_mfma_f32_16x16x32_bf16 v[112:115], v[192:195], v[200:203], v[112:115]
	s_setprio 0
	s_add_i32 s48, s62, s3
	s_add_i32 m0, s48, 0xffffff80
	ds_read_b128 v[196:199], v159 offset:49152
	ds_read_b128 v[200:203], v159 offset:50176
	ds_read_b128 v[204:207], v159 offset:51200
	ds_read_b128 v[208:211], v159 offset:52224
	ds_read_b128 v[212:215], v159 offset:53248
	ds_read_b128 v[216:219], v159 offset:54272
	ds_read_b128 v[220:223], v159 offset:55296
	ds_read_b128 v[224:227], v159 offset:56320
	global_load_lds_dwordx4 v130, s[46:47] offset:128
	s_add_i32 m0, s48, 0x1f80
	s_mov_b64 s[98:99], s[46:47]
	s_add_u32 s46, s46, 0x80080
	s_addc_u32 s47, s47, 0
	s_add_i32 s48, s63, s3
	global_load_lds_dwordx4 v134, s[98:99] offset:128
	s_mov_b32 m0, s48
	s_nop 0
	global_load_lds_dwordx4 v130, s[46:47]
	s_add_i32 m0, s48, 0x2000
	s_nop 0
	global_load_lds_dwordx4 v134, s[46:47]
	s_add_i32 m0, s55, 0xffffff80
	s_nop 0
	global_load_lds_dwordx4 v128, s[100:101] offset:128
	s_add_i32 m0, s56, 0xffffff80
	s_nop 0
	global_load_lds_dwordx4 v132, s[100:101] offset:128
	s_waitcnt vmcnt(8)
	s_waitcnt lgkmcnt(0)
	s_setprio 1
	s_barrier
	v_mfma_f32_16x16x32_bf16 v[60:63], v[164:167], v[196:199], v[60:63]
	v_mfma_f32_16x16x32_bf16 v[60:63], v[168:171], v[200:203], v[60:63]
	v_mfma_f32_16x16x32_bf16 v[44:47], v[164:167], v[204:207], v[44:47]
	v_mfma_f32_16x16x32_bf16 v[44:47], v[168:171], v[208:211], v[44:47]
	v_mfma_f32_16x16x32_bf16 v[28:31], v[164:167], v[212:215], v[28:31]
	v_mfma_f32_16x16x32_bf16 v[28:31], v[168:171], v[216:219], v[28:31]
	v_mfma_f32_16x16x32_bf16 v[12:15], v[164:167], v[220:223], v[12:15]
	v_mfma_f32_16x16x32_bf16 v[12:15], v[168:171], v[224:227], v[12:15]
	v_mfma_f32_16x16x32_bf16 v[8:11], v[172:175], v[220:223], v[8:11]
	v_mfma_f32_16x16x32_bf16 v[8:11], v[176:179], v[224:227], v[8:11]
	v_mfma_f32_16x16x32_bf16 v[24:27], v[172:175], v[212:215], v[24:27]
	v_mfma_f32_16x16x32_bf16 v[24:27], v[176:179], v[216:219], v[24:27]
	v_mfma_f32_16x16x32_bf16 v[40:43], v[172:175], v[204:207], v[40:43]
	v_mfma_f32_16x16x32_bf16 v[40:43], v[176:179], v[208:211], v[40:43]
	v_mfma_f32_16x16x32_bf16 v[56:59], v[172:175], v[196:199], v[56:59]
	v_mfma_f32_16x16x32_bf16 v[56:59], v[176:179], v[200:203], v[56:59]
	v_mfma_f32_16x16x32_bf16 v[52:55], v[180:183], v[196:199], v[52:55]
	v_mfma_f32_16x16x32_bf16 v[52:55], v[184:187], v[200:203], v[52:55]
	v_mfma_f32_16x16x32_bf16 v[36:39], v[180:183], v[204:207], v[36:39]
	v_mfma_f32_16x16x32_bf16 v[36:39], v[184:187], v[208:211], v[36:39]
	v_mfma_f32_16x16x32_bf16 v[20:23], v[180:183], v[212:215], v[20:23]
	v_mfma_f32_16x16x32_bf16 v[20:23], v[184:187], v[216:219], v[20:23]
	v_mfma_f32_16x16x32_bf16 v[4:7], v[180:183], v[220:223], v[4:7]
	v_mfma_f32_16x16x32_bf16 v[4:7], v[184:187], v[224:227], v[4:7]
	v_mfma_f32_16x16x32_bf16 v[0:3], v[188:191], v[220:223], v[0:3]
	v_mfma_f32_16x16x32_bf16 v[0:3], v[192:195], v[224:227], v[0:3]
	v_mfma_f32_16x16x32_bf16 v[16:19], v[188:191], v[212:215], v[16:19]
	v_mfma_f32_16x16x32_bf16 v[16:19], v[192:195], v[216:219], v[16:19]
	s_setprio 2
	s_barrier
	v_mfma_f32_16x16x32_bf16 v[32:35], v[188:191], v[204:207], v[32:35]
	v_mfma_f32_16x16x32_bf16 v[32:35], v[192:195], v[208:211], v[32:35]
	v_mfma_f32_16x16x32_bf16 v[48:51], v[188:191], v[196:199], v[48:51]
	v_mfma_f32_16x16x32_bf16 v[48:51], v[192:195], v[200:203], v[48:51]
	s_setprio 0
	s_add_i32 s67, s67, 2
	s_add_u32 s44, s44, 0x100
	s_addc_u32 s45, s45, 0
	s_add_u32 s65, s65, 0x100
	s_addc_u32 s66, s66, 0
	s_cmp_gt_u32 s67, 29
	s_cbranch_scc0 .LBB0_700
	s_and_b64 vcc, exec, s[12:13]
	s_cbranch_vccz .LBB0_703
	s_barrier

; #define PG8_STAGE(bufoff, gbase, voff) do { _Pragma("unroll") for (int _i = 0; _i < 2; ++_i) \
;         __builtin_amdgcn_global_load_lds((const unsigned*)((const char*)(gbase) + (voff)[_i]), (PG8_LAS unsigned*)(lds + (bufoff) + ldsw + _i * 8192), 16, 0, 0); } while (0)
; #define PG8_LDA(dst, b, h) do { _Pragma("unroll") for (int m = 0; m < 4; ++m) _Pragma("unroll") for (int k = 0; k < 2; ++k) dst[m][k] = *(const PG8_LAS bf16x8*)(lds + PG8_SA(b, h) + aoff + m * 2048 + k * 1024); } while (0)
; #define PG8_LDB(dst, b, h) do { _Pragma("unroll") for (int n = 0; n < 2; ++n) _Pragma("unroll") for (int k = 0; k < 2; ++k) dst[n][k] = *(const PG8_LAS bf16x8*)(lds + PG8_SB(b, h) + boff + n * 2048 + k * 1024); } while (0)
; #define PG8_MMA(ai, bj, At, Bt) do { __builtin_amdgcn_s_setprio(1); _Pragma("unroll") for (int m = 0; m < 4; ++m) _Pragma("unroll") for (int n = 0; n < 2; ++n) _Pragma("unroll") for (int k = 0; k < 2; ++k) \
;         acc[ai][bj][m][n] = __builtin_amdgcn_mfma_f32_16x16x32_bf16(Bt[n][k], At[m][k], acc[ai][bj][m][n], 0, 0, 0); __builtin_amdgcn_s_setprio(0); } while (0)
; #define PG8_WAIT_V(n) asm volatile("s_waitcnt vmcnt(" #n ")" ::: "memory")
; #define PG8_WAIT_L(n) asm volatile("s_waitcnt lgkmcnt(" #n ")" ::: "memory")
; template <class Epi, class Sched, bool ALIGN_EPI = false, bool SP2 = false>
; __device__ __forceinline__ void gemm_phase(PG8_LAS unsigned char* lds, const Gemm g, const Sched& S, const Epi& E) {
;     ...
;             const bool last = (t == nt - 2);
;             const char* a1 = cA + (size_t)(t + 1) * kstep;
;             const char* a2 = last ? nA : cA + (size_t)(t + 2) * kstep; const char* b2 = last ? nB : cB + (size_t)(t + 2) * kstep;
;             const char* a3 = a2 + kstep; const char* b3 = b2 + kstep;
;             if (last && has_next) S.a_ready(nxt);
;             if constexpr (SP2) {
;             PG8_LDB(B0, 0, 0); PG8_LDB(B1, 0, 1); PG8_SCHED; PG8_LDA(At, 0, 0); PG8_STAGE(PG8_SA(1, 1), a1 + hstep, voffA);
;             PG8_WAIT_V(8); PG8_WAIT_L(0); PG8_BAR; PG8_MMA(0, 0, At, B0); PG8_MMA(0, 1, At, B1); PG8_BAR; PG8_SCHED;
;             PG8_LDA(At, 0, 1); PG8_STAGE(PG8_SB(0, 0), b2, voffB); PG8_STAGE(PG8_SB(0, 1), b2 + hstep, voffB); PG8_STAGE(PG8_SA(0, 0), a2, voffA);
;             PG8_WAIT_V(8); PG8_WAIT_L(0); PG8_BAR; PG8_MMA(1, 0, At, B0); PG8_MMA(1, 1, At, B1); PG8_BAR; PG8_SCHED;
.LBB0_779:
	ds_read_b128 v[144:147], v155
	ds_read_b128 v[160:163], v155 offset:1024
	ds_read_b128 v[164:167], v155 offset:2048
	ds_read_b128 v[168:171], v155 offset:3072
	ds_read_b128 v[172:175], v156
	ds_read_b128 v[176:179], v156 offset:1024
	ds_read_b128 v[180:183], v156 offset:2048
	ds_read_b128 v[184:187], v156 offset:3072
	s_add_u32 s40, s38, 0xffea0080
	s_addc_u32 s41, s39, -1
	s_cmpk_eq_i32 s58, 0x54
	s_cselect_b32 s43, s7, s41
	s_cselect_b32 s42, s6, s40
	s_cselect_b32 s41, s37, s57
	s_cselect_b32 s40, s36, s11
	s_add_i32 m0, s33, 0xc000
	ds_read_b128 v[188:191], v157
	ds_read_b128 v[192:195], v157 offset:1024
	ds_read_b128 v[196:199], v157 offset:2048
	ds_read_b128 v[200:203], v157 offset:3072
	ds_read_b128 v[204:207], v157 offset:4096
	ds_read_b128 v[208:211], v157 offset:5120
	ds_read_b128 v[212:215], v157 offset:6144
	ds_read_b128 v[216:219], v157 offset:7168
	global_load_lds_dwordx4 v136, s[38:39]
	s_add_i32 m0, s33, 0xe000
	s_nop 0
	global_load_lds_dwordx4 v138, s[38:39]
	s_waitcnt vmcnt(8)
	s_waitcnt lgkmcnt(0)
	s_setprio 1
	s_barrier
	v_mfma_f32_16x16x32_bf16 v[124:127], v[144:147], v[188:191], v[124:127]
	v_mfma_f32_16x16x32_bf16 v[124:127], v[160:163], v[192:195], v[124:127]
	v_mfma_f32_16x16x32_bf16 v[108:111], v[144:147], v[196:199], v[108:111]
	v_mfma_f32_16x16x32_bf16 v[108:111], v[160:163], v[200:203], v[108:111]
	v_mfma_f32_16x16x32_bf16 v[92:95], v[144:147], v[204:207], v[92:95]
	v_mfma_f32_16x16x32_bf16 v[92:95], v[160:163], v[208:211], v[92:95]
	v_mfma_f32_16x16x32_bf16 v[76:79], v[144:147], v[212:215], v[76:79]
	v_mfma_f32_16x16x32_bf16 v[76:79], v[160:163], v[216:219], v[76:79]
	v_mfma_f32_16x16x32_bf16 v[72:75], v[164:167], v[212:215], v[72:75]
	v_mfma_f32_16x16x32_bf16 v[72:75], v[168:171], v[216:219], v[72:75]
	v_mfma_f32_16x16x32_bf16 v[88:91], v[164:167], v[204:207], v[88:91]
	v_mfma_f32_16x16x32_bf16 v[88:91], v[168:171], v[208:211], v[88:91]
	v_mfma_f32_16x16x32_bf16 v[104:107], v[164:167], v[196:199], v[104:107]
	v_mfma_f32_16x16x32_bf16 v[104:107], v[168:171], v[200:203], v[104:107]
	v_mfma_f32_16x16x32_bf16 v[120:123], v[164:167], v[188:191], v[120:123]
	v_mfma_f32_16x16x32_bf16 v[120:123], v[168:171], v[192:195], v[120:123]
	v_mfma_f32_16x16x32_bf16 v[116:119], v[172:175], v[188:191], v[116:119]
	v_mfma_f32_16x16x32_bf16 v[116:119], v[176:179], v[192:195], v[116:119]
	v_mfma_f32_16x16x32_bf16 v[100:103], v[172:175], v[196:199], v[100:103]
	v_mfma_f32_16x16x32_bf16 v[100:103], v[176:179], v[200:203], v[100:103]
	v_mfma_f32_16x16x32_bf16 v[84:87], v[172:175], v[204:207], v[84:87]
	v_mfma_f32_16x16x32_bf16 v[84:87], v[176:179], v[208:211], v[84:87]
	v_mfma_f32_16x16x32_bf16 v[68:71], v[172:175], v[212:215], v[68:71]
	v_mfma_f32_16x16x32_bf16 v[68:71], v[176:179], v[216:219], v[68:71]
	v_mfma_f32_16x16x32_bf16 v[64:67], v[180:183], v[212:215], v[64:67]
	v_mfma_f32_16x16x32_bf16 v[64:67], v[184:187], v[216:219], v[64:67]
	v_mfma_f32_16x16x32_bf16 v[80:83], v[180:183], v[204:207], v[80:83]
	v_mfma_f32_16x16x32_bf16 v[80:83], v[184:187], v[208:211], v[80:83]
	s_setprio 2
	s_barrier
	v_mfma_f32_16x16x32_bf16 v[96:99], v[180:183], v[196:199], v[96:99]
	v_mfma_f32_16x16x32_bf16 v[96:99], v[184:187], v[200:203], v[96:99]
	v_mfma_f32_16x16x32_bf16 v[112:115], v[180:183], v[188:191], v[112:115]
	v_mfma_f32_16x16x32_bf16 v[112:115], v[184:187], v[192:195], v[112:115]
	s_setprio 0
	s_add_i32 s59, s52, s3
	s_mov_b32 m0, s59
	ds_read_b128 v[188:191], v157 offset:16384
	ds_read_b128 v[192:195], v157 offset:17408
	ds_read_b128 v[196:199], v157 offset:18432
	ds_read_b128 v[200:203], v157 offset:19456
	ds_read_b128 v[204:207], v157 offset:20480
	ds_read_b128 v[208:211], v157 offset:21504
	ds_read_b128 v[212:215], v157 offset:22528
	ds_read_b128 v[216:219], v157 offset:23552
	global_load_lds_dwordx4 v130, s[40:41]
	s_add_i32 m0, s59, 0x2000
	s_add_u32 s62, s40, 0x160000
	s_addc_u32 s63, s41, 0
	s_add_i32 s59, s53, s3
	global_load_lds_dwordx4 v134, s[40:41]
	s_mov_b32 m0, s59
	s_nop 0
	global_load_lds_dwordx4 v130, s[62:63]
	s_add_i32 m0, s59, 0x2000
	s_nop 0
	global_load_lds_dwordx4 v134, s[62:63]
	s_mov_b32 m0, s33
	s_nop 0
	global_load_lds_dwordx4 v128, s[42:43]
	s_mov_b32 m0, s35
	s_nop 0
	global_load_lds_dwordx4 v132, s[42:43]
	s_waitcnt vmcnt(8)
	s_waitcnt lgkmcnt(0)
	s_setprio 1
	s_barrier
	v_mfma_f32_16x16x32_bf16 v[60:63], v[144:147], v[188:191], v[60:63]
	v_mfma_f32_16x16x32_bf16 v[60:63], v[160:163], v[192:195], v[60:63]
	v_mfma_f32_16x16x32_bf16 v[44:47], v[144:147], v[196:199], v[44:47]
	v_mfma_f32_16x16x32_bf16 v[44:47], v[160:163], v[200:203], v[44:47]
	v_mfma_f32_16x16x32_bf16 v[28:31], v[144:147], v[204:207], v[28:31]
	v_mfma_f32_16x16x32_bf16 v[28:31], v[160:163], v[208:211], v[28:31]
	v_mfma_f32_16x16x32_bf16 v[12:15], v[144:147], v[212:215], v[12:15]
	v_mfma_f32_16x16x32_bf16 v[12:15], v[160:163], v[216:219], v[12:15]
	v_mfma_f32_16x16x32_bf16 v[8:11], v[164:167], v[212:215], v[8:11]
	v_mfma_f32_16x16x32_bf16 v[8:11], v[168:171], v[216:219], v[8:11]
	v_mfma_f32_16x16x32_bf16 v[24:27], v[164:167], v[204:207], v[24:27]
	v_mfma_f32_16x16x32_bf16 v[24:27], v[168:171], v[208:211], v[24:27]
	v_mfma_f32_16x16x32_bf16 v[40:43], v[164:167], v[196:199], v[40:43]
	v_mfma_f32_16x16x32_bf16 v[40:43], v[168:171], v[200:203], v[40:43]
	v_mfma_f32_16x16x32_bf16 v[56:59], v[164:167], v[188:191], v[56:59]
	v_mfma_f32_16x16x32_bf16 v[56:59], v[168:171], v[192:195], v[56:59]
	v_mfma_f32_16x16x32_bf16 v[52:55], v[172:175], v[188:191], v[52:55]
	v_mfma_f32_16x16x32_bf16 v[52:55], v[176:179], v[192:195], v[52:55]
	v_mfma_f32_16x16x32_bf16 v[36:39], v[172:175], v[196:199], v[36:39]
	v_mfma_f32_16x16x32_bf16 v[36:39], v[176:179], v[200:203], v[36:39]
	v_mfma_f32_16x16x32_bf16 v[20:23], v[172:175], v[204:207], v[20:23]
	v_mfma_f32_16x16x32_bf16 v[20:23], v[176:179], v[208:211], v[20:23]
	v_mfma_f32_16x16x32_bf16 v[4:7], v[172:175], v[212:215], v[4:7]
	v_mfma_f32_16x16x32_bf16 v[4:7], v[176:179], v[216:219], v[4:7]
	v_mfma_f32_16x16x32_bf16 v[0:3], v[180:183], v[212:215], v[0:3]
	v_mfma_f32_16x16x32_bf16 v[0:3], v[184:187], v[216:219], v[0:3]
	v_mfma_f32_16x16x32_bf16 v[16:19], v[180:183], v[204:207], v[16:19]
	v_mfma_f32_16x16x32_bf16 v[16:19], v[184:187], v[208:211], v[16:19]
	s_setprio 2
	s_barrier
; #define PG8_STAGE(bufoff, gbase, voff) do { _Pragma("unroll") for (int _i = 0; _i < 2; ++_i) \
;         __builtin_amdgcn_global_load_lds((const unsigned*)((const char*)(gbase) + (voff)[_i]), (PG8_LAS unsigned*)(lds + (bufoff) + ldsw + _i * 8192), 16, 0, 0); } while (0)
; #define PG8_LDA(dst, b, h) do { _Pragma("unroll") for (int m = 0; m < 4; ++m) _Pragma("unroll") for (int k = 0; k < 2; ++k) dst[m][k] = *(const PG8_LAS bf16x8*)(lds + PG8_SA(b, h) + aoff + m * 2048 + k * 1024); } while (0)
; #define PG8_LDB(dst, b, h) do { _Pragma("unroll") for (int n = 0; n < 2; ++n) _Pragma("unroll") for (int k = 0; k < 2; ++k) dst[n][k] = *(const PG8_LAS bf16x8*)(lds + PG8_SB(b, h) + boff + n * 2048 + k * 1024); } while (0)
; #define PG8_MMA(ai, bj, At, Bt) do { __builtin_amdgcn_s_setprio(1); _Pragma("unroll") for (int m = 0; m < 4; ++m) _Pragma("unroll") for (int n = 0; n < 2; ++n) _Pragma("unroll") for (int k = 0; k < 2; ++k) \
;         acc[ai][bj][m][n] = __builtin_amdgcn_mfma_f32_16x16x32_bf16(Bt[n][k], At[m][k], acc[ai][bj][m][n], 0, 0, 0); __builtin_amdgcn_s_setprio(0); } while (0)
; #define PG8_WAIT_V(n) asm volatile("s_waitcnt vmcnt(" #n ")" ::: "memory")
; #define PG8_WAIT_L(n) asm volatile("s_waitcnt lgkmcnt(" #n ")" ::: "memory")
; #define PG8_BAR __builtin_amdgcn_s_barrier()
; #define PG8_SCHED __builtin_amdgcn_sched_barrier(0)
; template <class Epi, class Sched, bool ALIGN_EPI = false, bool SP2 = false>
; __device__ __forceinline__ void gemm_phase(PG8_LAS unsigned char* lds, const Gemm g, const Sched& S, const Epi& E) {
;     ...
;             PG8_LDB(B0, 1, 0); PG8_LDB(B1, 1, 1); PG8_SCHED; PG8_LDA(At, 1, 0); PG8_STAGE(PG8_SA(0, 1), a2 + hstep, voffA);
;             PG8_WAIT_V(8); PG8_WAIT_L(0); PG8_BAR; PG8_MMA(0, 0, At, B0); PG8_MMA(0, 1, At, B1); PG8_BAR; PG8_SCHED;
	v_mfma_f32_16x16x32_bf16 v[32:35], v[180:183], v[196:199], v[32:35]
	v_mfma_f32_16x16x32_bf16 v[32:35], v[184:187], v[200:203], v[32:35]
	v_mfma_f32_16x16x32_bf16 v[48:51], v[180:183], v[188:191], v[48:51]
	v_mfma_f32_16x16x32_bf16 v[48:51], v[184:187], v[192:195], v[48:51]
	s_setprio 0
	s_add_i32 s59, 0, 0x18000
	s_add_i32 s61, 0, 0x1c000
	ds_read_b128 v[144:147], v155 offset:32768
	ds_read_b128 v[160:163], v155 offset:33792
	ds_read_b128 v[164:167], v155 offset:34816
	ds_read_b128 v[168:171], v155 offset:35840
	ds_read_b128 v[172:175], v156 offset:32768
	ds_read_b128 v[176:179], v156 offset:33792
	ds_read_b128 v[180:183], v156 offset:34816
	ds_read_b128 v[184:187], v156 offset:35840
	s_mov_b64 s[100:101], s[42:43]
	s_add_u32 s42, s42, 0x160000
	s_addc_u32 s43, s43, 0
	s_mov_b32 m0, s44
	ds_read_b128 v[188:191], v157 offset:32768
	ds_read_b128 v[192:195], v157 offset:33792
	ds_read_b128 v[196:199], v157 offset:34816
	ds_read_b128 v[200:203], v157 offset:35840
	ds_read_b128 v[204:207], v157 offset:36864
	ds_read_b128 v[208:211], v157 offset:37888
	ds_read_b128 v[212:215], v157 offset:38912
	ds_read_b128 v[216:219], v157 offset:39936
	global_load_lds_dwordx4 v128, s[42:43]
	s_mov_b32 m0, s45
	s_nop 0
	global_load_lds_dwordx4 v132, s[42:43]
	s_waitcnt vmcnt(8)
	s_waitcnt lgkmcnt(0)
	s_setprio 1
	s_barrier
	v_mfma_f32_16x16x32_bf16 v[124:127], v[144:147], v[188:191], v[124:127]
	v_mfma_f32_16x16x32_bf16 v[124:127], v[160:163], v[192:195], v[124:127]
	v_mfma_f32_16x16x32_bf16 v[108:111], v[144:147], v[196:199], v[108:111]
	v_mfma_f32_16x16x32_bf16 v[108:111], v[160:163], v[200:203], v[108:111]
	v_mfma_f32_16x16x32_bf16 v[92:95], v[144:147], v[204:207], v[92:95]
	v_mfma_f32_16x16x32_bf16 v[92:95], v[160:163], v[208:211], v[92:95]
	v_mfma_f32_16x16x32_bf16 v[76:79], v[144:147], v[212:215], v[76:79]
	v_mfma_f32_16x16x32_bf16 v[76:79], v[160:163], v[216:219], v[76:79]
	v_mfma_f32_16x16x32_bf16 v[72:75], v[164:167], v[212:215], v[72:75]
	v_mfma_f32_16x16x32_bf16 v[72:75], v[168:171], v[216:219], v[72:75]
	v_mfma_f32_16x16x32_bf16 v[88:91], v[164:167], v[204:207], v[88:91]
	v_mfma_f32_16x16x32_bf16 v[88:91], v[168:171], v[208:211], v[88:91]
	v_mfma_f32_16x16x32_bf16 v[104:107], v[164:167], v[196:199], v[104:107]
	v_mfma_f32_16x16x32_bf16 v[104:107], v[168:171], v[200:203], v[104:107]
	v_mfma_f32_16x16x32_bf16 v[120:123], v[164:167], v[188:191], v[120:123]
	v_mfma_f32_16x16x32_bf16 v[120:123], v[168:171], v[192:195], v[120:123]
	v_mfma_f32_16x16x32_bf16 v[116:119], v[172:175], v[188:191], v[116:119]
	v_mfma_f32_16x16x32_bf16 v[116:119], v[176:179], v[192:195], v[116:119]
	v_mfma_f32_16x16x32_bf16 v[100:103], v[172:175], v[196:199], v[100:103]
	v_mfma_f32_16x16x32_bf16 v[100:103], v[176:179], v[200:203], v[100:103]
	v_mfma_f32_16x16x32_bf16 v[84:87], v[172:175], v[204:207], v[84:87]
	v_mfma_f32_16x16x32_bf16 v[84:87], v[176:179], v[208:211], v[84:87]
	v_mfma_f32_16x16x32_bf16 v[68:71], v[172:175], v[212:215], v[68:71]
	v_mfma_f32_16x16x32_bf16 v[68:71], v[176:179], v[216:219], v[68:71]
	v_mfma_f32_16x16x32_bf16 v[64:67], v[180:183], v[212:215], v[64:67]
	v_mfma_f32_16x16x32_bf16 v[64:67], v[184:187], v[216:219], v[64:67]
	v_mfma_f32_16x16x32_bf16 v[80:83], v[180:183], v[204:207], v[80:83]
	v_mfma_f32_16x16x32_bf16 v[80:83], v[184:187], v[208:211], v[80:83]
	s_setprio 2
	s_barrier
; #define PG8_STAGE(bufoff, gbase, voff) do { _Pragma("unroll") for (int _i = 0; _i < 2; ++_i) \
;         __builtin_amdgcn_global_load_lds((const unsigned*)((const char*)(gbase) + (voff)[_i]), (PG8_LAS unsigned*)(lds + (bufoff) + ldsw + _i * 8192), 16, 0, 0); } while (0)
; #define PG8_LDA(dst, b, h) do { _Pragma("unroll") for (int m = 0; m < 4; ++m) _Pragma("unroll") for (int k = 0; k < 2; ++k) dst[m][k] = *(const PG8_LAS bf16x8*)(lds + PG8_SA(b, h) + aoff + m * 2048 + k * 1024); } while (0)
; #define PG8_MMA(ai, bj, At, Bt) do { __builtin_amdgcn_s_setprio(1); _Pragma("unroll") for (int m = 0; m < 4; ++m) _Pragma("unroll") for (int n = 0; n < 2; ++n) _Pragma("unroll") for (int k = 0; k < 2; ++k) \
;         acc[ai][bj][m][n] = __builtin_amdgcn_mfma_f32_16x16x32_bf16(Bt[n][k], At[m][k], acc[ai][bj][m][n], 0, 0, 0); __builtin_amdgcn_s_setprio(0); } while (0)
; #define PG8_WAIT_V(n) asm volatile("s_waitcnt vmcnt(" #n ")" ::: "memory")
; #define PG8_WAIT_L(n) asm volatile("s_waitcnt lgkmcnt(" #n ")" ::: "memory")
; #define PG8_BAR __builtin_amdgcn_s_barrier()
; #define PG8_SCHED __builtin_amdgcn_sched_barrier(0)
; template <class Epi, class Sched, bool ALIGN_EPI = false, bool SP2 = false>
; __device__ __forceinline__ void gemm_phase(PG8_LAS unsigned char* lds, const Gemm g, const Sched& S, const Epi& E) {
;     ...
;         for (int t = 0; t < nt; t += 2) {
;     ...
;             PG8_LDA(At, 1, 1); PG8_STAGE(PG8_SB(1, 0), b3, voffB); PG8_STAGE(PG8_SB(1, 1), b3 + hstep, voffB); PG8_STAGE(PG8_SA(1, 0), a3, voffA);
;             PG8_WAIT_V(8); PG8_WAIT_L(0); PG8_BAR; PG8_MMA(1, 0, At, B0); PG8_MMA(1, 1, At, B1); PG8_BAR; PG8_SCHED;
	v_mfma_f32_16x16x32_bf16 v[96:99], v[180:183], v[196:199], v[96:99]
	v_mfma_f32_16x16x32_bf16 v[96:99], v[184:187], v[200:203], v[96:99]
	v_mfma_f32_16x16x32_bf16 v[112:115], v[180:183], v[188:191], v[112:115]
	v_mfma_f32_16x16x32_bf16 v[112:115], v[184:187], v[192:195], v[112:115]
	s_setprio 0
	s_add_i32 s42, s59, s3
	s_add_i32 m0, s42, 0xffffff80
	ds_read_b128 v[188:191], v157 offset:49152
	ds_read_b128 v[192:195], v157 offset:50176
	ds_read_b128 v[196:199], v157 offset:51200
	ds_read_b128 v[200:203], v157 offset:52224
	ds_read_b128 v[204:207], v157 offset:53248
	ds_read_b128 v[208:211], v157 offset:54272
	ds_read_b128 v[212:215], v157 offset:55296
	ds_read_b128 v[216:219], v157 offset:56320
	global_load_lds_dwordx4 v130, s[40:41] offset:128
	s_add_i32 m0, s42, 0x1f80
	s_mov_b64 s[98:99], s[40:41]
	s_add_u32 s40, s40, 0x160080
	s_addc_u32 s41, s41, 0
	s_add_i32 s42, s61, s3
	global_load_lds_dwordx4 v134, s[98:99] offset:128
	s_mov_b32 m0, s42
	s_nop 0
	global_load_lds_dwordx4 v130, s[40:41]
	s_add_i32 m0, s42, 0x2000
	s_nop 0
	global_load_lds_dwordx4 v134, s[40:41]
	s_add_i32 m0, s49, 0xffffff80
	s_nop 0
	global_load_lds_dwordx4 v128, s[100:101] offset:128
	s_add_i32 m0, s50, 0xffffff80
	s_nop 0
	global_load_lds_dwordx4 v132, s[100:101] offset:128
	s_waitcnt vmcnt(8)
	s_waitcnt lgkmcnt(0)
	s_setprio 1
	s_barrier
	v_mfma_f32_16x16x32_bf16 v[60:63], v[144:147], v[188:191], v[60:63]
	v_mfma_f32_16x16x32_bf16 v[60:63], v[160:163], v[192:195], v[60:63]
	v_mfma_f32_16x16x32_bf16 v[44:47], v[144:147], v[196:199], v[44:47]
	v_mfma_f32_16x16x32_bf16 v[44:47], v[160:163], v[200:203], v[44:47]
	v_mfma_f32_16x16x32_bf16 v[28:31], v[144:147], v[204:207], v[28:31]
	v_mfma_f32_16x16x32_bf16 v[28:31], v[160:163], v[208:211], v[28:31]
	v_mfma_f32_16x16x32_bf16 v[12:15], v[144:147], v[212:215], v[12:15]
	v_mfma_f32_16x16x32_bf16 v[12:15], v[160:163], v[216:219], v[12:15]
	v_mfma_f32_16x16x32_bf16 v[8:11], v[164:167], v[212:215], v[8:11]
	v_mfma_f32_16x16x32_bf16 v[8:11], v[168:171], v[216:219], v[8:11]
	v_mfma_f32_16x16x32_bf16 v[24:27], v[164:167], v[204:207], v[24:27]
	v_mfma_f32_16x16x32_bf16 v[24:27], v[168:171], v[208:211], v[24:27]
	v_mfma_f32_16x16x32_bf16 v[40:43], v[164:167], v[196:199], v[40:43]
	v_mfma_f32_16x16x32_bf16 v[40:43], v[168:171], v[200:203], v[40:43]
	v_mfma_f32_16x16x32_bf16 v[56:59], v[164:167], v[188:191], v[56:59]
	v_mfma_f32_16x16x32_bf16 v[56:59], v[168:171], v[192:195], v[56:59]
	v_mfma_f32_16x16x32_bf16 v[52:55], v[172:175], v[188:191], v[52:55]
	v_mfma_f32_16x16x32_bf16 v[52:55], v[176:179], v[192:195], v[52:55]
	v_mfma_f32_16x16x32_bf16 v[36:39], v[172:175], v[196:199], v[36:39]
	v_mfma_f32_16x16x32_bf16 v[36:39], v[176:179], v[200:203], v[36:39]
	v_mfma_f32_16x16x32_bf16 v[20:23], v[172:175], v[204:207], v[20:23]
	v_mfma_f32_16x16x32_bf16 v[20:23], v[176:179], v[208:211], v[20:23]
	v_mfma_f32_16x16x32_bf16 v[4:7], v[172:175], v[212:215], v[4:7]
	v_mfma_f32_16x16x32_bf16 v[4:7], v[176:179], v[216:219], v[4:7]
	v_mfma_f32_16x16x32_bf16 v[0:3], v[180:183], v[212:215], v[0:3]
	v_mfma_f32_16x16x32_bf16 v[0:3], v[184:187], v[216:219], v[0:3]
	v_mfma_f32_16x16x32_bf16 v[16:19], v[180:183], v[204:207], v[16:19]
	v_mfma_f32_16x16x32_bf16 v[16:19], v[184:187], v[208:211], v[16:19]
	s_setprio 2
	s_barrier
	v_mfma_f32_16x16x32_bf16 v[32:35], v[180:183], v[196:199], v[32:35]
	v_mfma_f32_16x16x32_bf16 v[32:35], v[184:187], v[200:203], v[32:35]
	v_mfma_f32_16x16x32_bf16 v[48:51], v[180:183], v[188:191], v[48:51]
	v_mfma_f32_16x16x32_bf16 v[48:51], v[184:187], v[192:195], v[48:51]
	s_setprio 0
	s_add_i32 s58, s58, 2
	s_add_u32 s38, s38, 0x100
	s_addc_u32 s39, s39, 0
	s_add_u32 s11, s11, 0x100
	s_addc_u32 s57, s57, 0
	s_cmpk_gt_u32 s58, 0x55
	s_cbranch_scc0 .LBB0_779
	s_and_b64 vcc, exec, s[20:21]
	s_cbranch_vccz .LBB0_782
	s_barrier
